# PEER gather loops: gathers interleaved one-per-row with counted vmcnt waits (ring), addresses precomputed in dead VGPRs
# speedup vs baseline: 1.0023x; 1.0023x over previous
; DI int otid_w(int wave) { unsigned z = 0u; asm volatile("" : "+v"(z)); int t = wave * 64 + (int)__builtin_amdgcn_mbcnt_hi(~0u, __builtin_amdgcn_mbcnt_lo(~0u, z)); asm volatile("" : "+v"(t)); return t; }
; #define PEER_META(T, IA, IB, HA, HB) do { const int _t = (T) < TTOK ? (T) : wslot; \
;     IA = *(const u32x4*)(W_IDX(p) + (size_t)_t * 128 + r * 16); IB = *(const u32x4*)(W_IDX(p) + (size_t)_t * 128 + r * 16 + 8); \
;     const u16* _hp = W_H(p) + (size_t)_t * DM + x * 128 + 16 * c; HA = *(const u32x4*)(_hp); HB = *(const u32x4*)(_hp + 8); } while (0)
; #define PEER_GATHER(TAB, IA, IB, RR) do { _Pragma("unroll") for (int g = 0; g < 16; ++g) { \
;     const unsigned _w = (g < 8 ? IA : IB)[(g >> 1) & 3]; RR[g] = *(const u32x4*)((TAB) + row_off(_w, c16, (g & 1) != 0)); } } while (0)
; DI void phase_peer_dots(const Params& p, int layer, int wave) {
;   const int tid = otid_w(wave), lane = tid & 63, wid = wave, c = lane & 7, r = lane >> 3;
;   const int x = blockIdx.x & 7, wslot = (blockIdx.x >> 3) * 8 + wid, nslot = (gridDim.x >> 3) * 8;
;   const unsigned char* ub = W_UB(p) + (size_t)x * (PEER_N * 128);
;   const unsigned c16 = (unsigned)c * 16u;
;   u16* pd = W_Y(p);
;   u32x4 iAa, iBa, iAb, iBb;
;   u32x4 hAa, hBa, hAb, hBb, rrA[16], rrB[16];
;   int xq[4];
;   float xscale;
;     ...
;   int t = wslot;
;   PEER_META(t, iAa, iBa, hAa, hBa);
;   PEER_META(t + nslot, iAb, iBb, hAb, hBb);
;   PEER_GATHER(ub, iAa, iBa, rrA);
.LBB0_125:
	s_and_b64 vcc, exec, s[0:1]
	s_cbranch_vccz .LBB0_133
	s_cmp_gt_i32 s96, 4
	s_mov_b64 s[56:57], -1
	s_cbranch_scc0 .LBB0_133
	s_waitcnt vmcnt(0)
	v_mov_b32_e32 v0, v177
	v_readlane_b32 s0, v253, 51
	v_mbcnt_lo_u32_b32 v0, -1, v0
	v_mbcnt_hi_u32_b32 v0, -1, v0
	v_add_u32_e32 v88, s64, v0
	v_readlane_b32 s1, v253, 52
	v_lshlrev_b32_e32 v0, 1, v88
	v_and_b32_e32 v0, 0x70, v0
	v_lshlrev_b32_e32 v176, 1, v0
	s_waitcnt lgkmcnt(0)
	s_nop 0
	global_load_dwordx4 v[4:7], v176, s[0:1]
	global_load_dwordx4 v[10:13], v176, s[0:1] offset:16
	v_readlane_b32 s0, v253, 56
	v_readlane_b32 s1, v253, 57
	v_and_b32_e32 v89, 7, v88
	s_andn2_b64 vcc, exec, s[0:1]
	v_lshlrev_b32_e32 v160, 4, v89
	s_waitcnt vmcnt(1)
	v_mad_u32_u16 v0, v4, v195, v160
	v_mad_u32_u16 v1, v4, v195, v160 op_sel:[1,0,0,0]
	v_mad_u32_u16 v2, v5, v195, v160
	v_mad_u32_u16 v3, v5, v195, v160 op_sel:[1,0,0,0]
	v_mad_u32_u16 v4, v6, v195, v160
	v_mad_u32_u16 v5, v6, v195, v160 op_sel:[1,0,0,0]
	v_mad_u32_u16 v6, v7, v195, v160
	v_mad_u32_u16 v7, v7, v195, v160 op_sel:[1,0,0,0]
	s_waitcnt vmcnt(0)
	v_mad_u32_u16 v8, v10, v195, v160
	v_mad_u32_u16 v9, v10, v195, v160 op_sel:[1,0,0,0]
	v_mad_u32_u16 v10, v11, v195, v160
	v_mad_u32_u16 v11, v11, v195, v160 op_sel:[1,0,0,0]
	v_mad_u32_u16 v16, v12, v195, v160
	v_mad_u32_u16 v12, v12, v195, v160 op_sel:[1,0,0,0]
	v_mad_u32_u16 v52, v13, v195, v160
	v_mad_u32_u16 v64, v13, v195, v160 op_sel:[1,0,0,0]
	s_cbranch_vccnz .LBB0_132
	global_load_dwordx4 v[12:15], v12, s[14:15]
	s_nop 0
	global_load_dwordx4 v[20:23], v16, s[14:15]
	global_load_dwordx4 v[24:27], v11, s[14:15]
	global_load_dwordx4 v[28:31], v10, s[14:15]
	global_load_dwordx4 v[32:35], v9, s[14:15]
	global_load_dwordx4 v[36:39], v8, s[14:15]
	global_load_dwordx4 v[40:43], v7, s[14:15]
	global_load_dwordx4 v[44:47], v6, s[14:15]
	global_load_dwordx4 v[48:51], v5, s[14:15]
	global_load_dwordx4 v[56:59], v4, s[14:15]
	global_load_dwordx4 v[60:63], v3, s[14:15]
	global_load_dwordx4 v[68:71], v2, s[14:15]
	global_load_dwordx4 v[72:75], v1, s[14:15]
	global_load_dwordx4 v[76:79], v0, s[14:15]
	v_readlane_b32 s0, v253, 60
	v_lshlrev_b32_e32 v90, 1, v160
	v_readlane_b32 s1, v253, 61
	s_nop 4
	global_load_dwordx4 v[0:3], v90, s[0:1] offset:16
	global_load_dwordx4 v[4:7], v90, s[0:1]
	v_readlane_b32 s0, v253, 62
	v_readlane_b32 s1, v253, 63
	s_nop 4
	global_load_dwordx4 v[80:83], v176, s[0:1] offset:16
	global_load_dwordx4 v[84:87], v176, s[0:1]
	v_readlane_b32 s0, v254, 2
	v_readlane_b32 s1, v254, 3
	s_nop 4
	global_load_dwordx4 v[8:11], v90, s[0:1] offset:16
	global_load_dwordx4 v[16:19], v90, s[0:1]
	s_nop 0
	global_load_dwordx4 v[52:55], v52, s[14:15]
	s_nop 0
	global_load_dwordx4 v[64:67], v64, s[14:15]
	v_readlane_b32 s0, v253, 54
	v_mov_b32_e32 v91, v177
	v_readlane_b32 s1, v253, 55
	v_readlane_b32 s12, v254, 4
	v_readlane_b32 s13, v254, 5
	v_lshl_add_u64 v[164:165], s[0:1], 0, v[90:91]
	v_and_b32_e32 v90, 2, v88
	v_cmp_eq_u32_e64 s[4:5], 0, v90
	v_and_b32_e32 v90, 1, v88
	v_lshl_add_u64 v[162:163], s[66:67], 0, v[176:177]
	v_cmp_eq_u32_e64 s[6:7], 0, v90
	v_lshl_add_u64 v[90:91], s[12:13], 0, v[176:177]
	v_lshlrev_b32_e32 v176, 1, v89
	v_lshlrev_b32_e32 v88, 2, v88
	s_movk_i32 s12, 0xe0
	v_lshl_add_u64 v[166:167], v[90:91], 0, v[176:177]
	v_and_or_b32 v176, v88, s12, v176
	v_readlane_b32 s12, v255, 14
	v_readlane_b32 s13, v255, 15
	v_cmp_lt_u32_e64 s[0:1], 3, v89
	s_nop 0
	v_lshl_add_u64 v[168:169], s[12:13], 0, v[176:177]
	s_mov_b32 s12, s38
	s_waitcnt vmcnt(0)
	s_branch .LBB0_130

; #define PEER_META(T, IA, IB, HA, HB) do { const int _t = (T) < TTOK ? (T) : wslot; \
;     IA = *(const u32x4*)(W_IDX(p) + (size_t)_t * 128 + r * 16); IB = *(const u32x4*)(W_IDX(p) + (size_t)_t * 128 + r * 16 + 8); \
;     const u16* _hp = W_H(p) + (size_t)_t * DM + x * 128 + 16 * c; HA = *(const u32x4*)(_hp); HB = *(const u32x4*)(_hp + 8); } while (0)
; #define PEER_GATHER(TAB, IA, IB, RR) do { _Pragma("unroll") for (int g = 0; g < 16; ++g) { \
;     const unsigned _w = (g < 8 ? IA : IB)[(g >> 1) & 3]; RR[g] = *(const u32x4*)((TAB) + row_off(_w, c16, (g & 1) != 0)); } } while (0)
; DI void phase_peer_dots(const Params& p, int layer, int wave) {
;     ...
;   for (; t < TTOK; t += 2 * nslot) {
;     DOTS_QUANT(hAa, hBa);
;     PEER_META(t + 2 * nslot, iAa, iBa, hAa, hBa);
;     PEER_GATHER(ub, iAb, iBb, rrB);
.LBB0_130:
	s_add_i32 s100, s12, s88
	s_cmp_lt_i32 s100, 0x10200
	s_cselect_b32 s100, s100, s38
	s_ashr_i32 s101, s100, 31
	s_lshl_b64 s[100:101], s[100:101], 8
	v_lshl_add_u64 v[222:223], v[162:163], 0, s[100:101]
	global_load_dwordx4 v[152:155], v[222:223], off offset:16
	global_load_dwordx4 v[156:159], v[222:223], off
	s_waitcnt vmcnt(21)
	v_mad_u32_u16 v206, v84, v195, v160
	v_mad_u32_u16 v207, v84, v195, v160 op_sel:[1,0,0,0]
	v_mad_u32_u16 v208, v85, v195, v160
	v_mad_u32_u16 v209, v85, v195, v160 op_sel:[1,0,0,0]
	v_mad_u32_u16 v210, v86, v195, v160
	v_mad_u32_u16 v211, v86, v195, v160 op_sel:[1,0,0,0]
	v_mad_u32_u16 v212, v87, v195, v160
	v_mad_u32_u16 v213, v87, v195, v160 op_sel:[1,0,0,0]
	v_mad_u32_u16 v214, v80, v195, v160
	v_mad_u32_u16 v215, v80, v195, v160 op_sel:[1,0,0,0]
	v_mad_u32_u16 v216, v81, v195, v160
	v_mad_u32_u16 v217, v81, v195, v160 op_sel:[1,0,0,0]
	v_mad_u32_u16 v218, v82, v195, v160
	v_mad_u32_u16 v219, v82, v195, v160 op_sel:[1,0,0,0]
	v_mad_u32_u16 v220, v83, v195, v160
	v_mad_u32_u16 v221, v83, v195, v160 op_sel:[1,0,0,0]
	v_lshlrev_b32_e32 v88, 16, v16
	v_and_b32_e32 v16, 0xffff0000, v16
	v_lshlrev_b32_e32 v90, 16, v17
	v_and_b32_e32 v17, 0xffff0000, v17
	v_max3_f32 v96, |v88|, 0, |v16|
	v_lshlrev_b32_e32 v92, 16, v18
	v_and_b32_e32 v18, 0xffff0000, v18
	global_load_dwordx4 v[148:151], v206, s[14:15]
	v_max3_f32 v96, v96, |v90|, |v17|
	v_lshlrev_b32_e32 v94, 16, v19
	v_and_b32_e32 v19, 0xffff0000, v19
	v_max3_f32 v96, v96, |v92|, |v18|
	v_lshlrev_b32_e32 v89, 16, v8
	v_and_b32_e32 v8, 0xffff0000, v8
	v_max3_f32 v96, v96, |v94|, |v19|
	v_lshlrev_b32_e32 v91, 16, v9
	v_and_b32_e32 v9, 0xffff0000, v9
	v_max3_f32 v96, v96, |v89|, |v8|
	v_lshlrev_b32_e32 v93, 16, v10
	v_and_b32_e32 v10, 0xffff0000, v10
	v_max3_f32 v96, v96, |v91|, |v9|
	v_lshlrev_b32_e32 v95, 16, v11
	v_and_b32_e32 v11, 0xffff0000, v11
	v_max3_f32 v96, v96, |v93|, |v10|
	global_load_dwordx4 v[140:143], v207, s[14:15]
	v_max3_f32 v96, v96, |v95|, |v11|
	s_mov_b32 s13, s12
	s_add_i32 s12, s12, s88
	v_mov_b32_dpp v97, v96 quad_perm:[1,0,3,2] row_mask:0xf bank_mask:0xf bound_ctrl:1
	v_max_f32_e32 v97, v97, v97
	v_max_f32_e32 v96, v96, v97
	s_cmp_gt_i32 s12, 0x101ff
	s_cselect_b64 s[56:57], -1, 0
	v_mov_b32_dpp v97, v96 quad_perm:[2,3,0,1] row_mask:0xf bank_mask:0xf bound_ctrl:1
	v_max_f32_e32 v97, v97, v97
	v_max_f32_e32 v96, v96, v97
	s_cmp_lt_i32 s12, 0x10200
	s_waitcnt vmcnt(22)
	v_lshlrev_b32_e32 v179, 16, v0
	v_mov_b32_dpp v97, v96 row_half_mirror row_mask:0xf bank_mask:0xf bound_ctrl:1
	v_max_f32_e32 v97, v97, v97
	v_max_f32_e32 v161, v96, v97
	v_div_scale_f32 v96, s[28:29], v161, v161, s63
	v_rcp_f32_e32 v97, v96
	s_cselect_b32 s28, s12, s38
	s_ashr_i32 s29, s28, 31
	s_lshl_b64 s[36:37], s[28:29], 8
	v_fma_f32 v98, -v96, v97, 1.0
	v_fmac_f32_e32 v97, v98, v97
	v_div_scale_f32 v98, vcc, s63, v161, s63
	global_load_dwordx4 v[144:147], v208, s[14:15]
	v_mul_f32_e32 v99, v98, v97
	v_fma_f32 v100, -v96, v99, v98
	v_fmac_f32_e32 v99, v100, v97
	v_fma_f32 v96, -v96, v99, v98
	v_div_fmas_f32 v96, v96, v97, v99
	v_div_fixup_f32 v96, v96, v161, s63
	v_cmp_lt_f32_e32 vcc, 0, v161
	s_lshl_b64 s[28:29], s[28:29], 11
	s_add_i32 s21, s41, s13
	v_cndmask_b32_e32 v96, 0, v96, vcc
	v_mul_f32_e32 v16, v96, v16
	v_mul_f32_e32 v88, v96, v88
	v_rndne_f32_e32 v16, v16
	v_mul_f32_e32 v90, v96, v90
	v_rndne_f32_e32 v88, v88
	v_cvt_i32_f32_e32 v16, v16
	v_rndne_f32_e32 v90, v90
	global_load_dwordx4 v[132:135], v209, s[14:15]
	v_mul_f32_e32 v17, v96, v17
	v_cvt_i32_f32_e32 v88, v88
	v_cvt_i32_f32_sdwa v90, v90 dst_sel:WORD_1 dst_unused:UNUSED_PAD src0_sel:DWORD
	v_rndne_f32_e32 v17, v17
	v_cvt_i32_f32_sdwa v17, v17 dst_sel:BYTE_3 dst_unused:UNUSED_PAD src0_sel:DWORD
	v_lshlrev_b32_e32 v16, 8, v16
	v_perm_b32 v16, v16, v88, s72
	v_and_b32_e32 v88, 0xff0000, v90
	v_or3_b32 v170, v16, v88, v17
	v_mul_f32_e32 v17, v96, v18
	v_mul_f32_e32 v16, v96, v92
	v_rndne_f32_e32 v17, v17
	v_mul_f32_e32 v18, v96, v94
	v_rndne_f32_e32 v16, v16
	v_cvt_i32_f32_e32 v17, v17
	v_rndne_f32_e32 v18, v18
	global_load_dwordx4 v[136:139], v210, s[14:15]
	v_mul_f32_e32 v19, v96, v19
	v_cvt_i32_f32_e32 v16, v16
	v_cvt_i32_f32_sdwa v18, v18 dst_sel:WORD_1 dst_unused:UNUSED_PAD src0_sel:DWORD
	v_rndne_f32_e32 v19, v19
	v_cvt_i32_f32_sdwa v19, v19 dst_sel:BYTE_3 dst_unused:UNUSED_PAD src0_sel:DWORD
	v_lshlrev_b32_e32 v17, 8, v17
	v_perm_b32 v16, v17, v16, s72
	v_and_b32_e32 v17, 0xff0000, v18
	v_mul_f32_e32 v8, v96, v8
	v_or3_b32 v171, v16, v17, v19
	v_mul_f32_e32 v16, v96, v89
	v_rndne_f32_e32 v8, v8
	v_mul_f32_e32 v17, v96, v91
	v_rndne_f32_e32 v16, v16
	v_cvt_i32_f32_e32 v8, v8
	global_load_dwordx4 v[124:127], v211, s[14:15]
	v_rndne_f32_e32 v17, v17
	v_mul_f32_e32 v9, v96, v9
	v_cvt_i32_f32_e32 v16, v16
	v_cvt_i32_f32_sdwa v17, v17 dst_sel:WORD_1 dst_unused:UNUSED_PAD src0_sel:DWORD
	v_rndne_f32_e32 v9, v9
	v_cvt_i32_f32_sdwa v9, v9 dst_sel:BYTE_3 dst_unused:UNUSED_PAD src0_sel:DWORD
	v_lshlrev_b32_e32 v8, 8, v8
	v_perm_b32 v8, v8, v16, s72
	v_and_b32_e32 v16, 0xff0000, v17
	v_or3_b32 v172, v8, v16, v9
	v_mul_f32_e32 v9, v96, v10
	v_mul_f32_e32 v8, v96, v93
	v_rndne_f32_e32 v9, v9
	v_mul_f32_e32 v10, v96, v95
	v_rndne_f32_e32 v8, v8
	v_cvt_i32_f32_e32 v9, v9
	global_load_dwordx4 v[128:131], v212, s[14:15]
	v_rndne_f32_e32 v10, v10
	v_mul_f32_e32 v11, v96, v11
	v_cvt_i32_f32_e32 v8, v8
	v_cvt_i32_f32_sdwa v10, v10 dst_sel:WORD_1 dst_unused:UNUSED_PAD src0_sel:DWORD
	v_rndne_f32_e32 v11, v11
	v_cvt_i32_f32_sdwa v11, v11 dst_sel:BYTE_3 dst_unused:UNUSED_PAD src0_sel:DWORD
	v_lshlrev_b32_e32 v9, 8, v9
	v_perm_b32 v8, v9, v8, s72
	v_and_b32_e32 v9, 0xff0000, v10
	v_or3_b32 v173, v8, v9, v11
	v_lshl_add_u64 v[16:17], v[164:165], 0, s[28:29]
	global_load_dwordx4 v[8:11], v[16:17], off offset:16
	s_nop 0
	global_load_dwordx4 v[16:19], v[16:17], off
	s_nop 0
	v_mov_b32_e32 v80, v177
	v_dot4c_i32_i8_e32 v80, v76, v170
	v_mov_b32_e32 v76, v177
	s_waitcnt vmcnt(27)
; #define DPP_I(v, ctrl) __builtin_amdgcn_update_dpp(0, (v), (ctrl), 0xf, 0xf, true)
; DI int reduce_scatter8(int d0, int d1, int d2, int d3, int d4, int d5, int d6, int d7, int c) {
;   const bool b2 = c >= 4, b1 = (c & 2) != 0, b0 = (c & 1) != 0;
;   const int e0 = (b2 ? d4 : d0) + DPP_I(b2 ? d0 : d4, 0x141);
;   const int e1 = (b2 ? d5 : d1) + DPP_I(b2 ? d1 : d5, 0x141);
;   const int e2 = (b2 ? d6 : d2) + DPP_I(b2 ? d2 : d6, 0x141);
;   const int e3 = (b2 ? d7 : d3) + DPP_I(b2 ? d3 : d7, 0x141);
;   const int f0 = (b1 ? e2 : e0) + DPP_I(b1 ? e0 : e2, 0x4E);
;   const int f1 = (b1 ? e3 : e1) + DPP_I(b1 ? e1 : e3, 0x4E);
;   return (b0 ? f1 : f0) + DPP_I(b0 ? f0 : f1, 0xB1);
; }
	v_dot4c_i32_i8_e32 v76, v72, v170
	v_mov_b32_e32 v72, v177
	global_load_dwordx4 v[116:119], v213, s[14:15]
	s_waitcnt vmcnt(27)
	v_dot4c_i32_i8_e32 v72, v68, v170
	v_mov_b32_e32 v68, v177
	s_waitcnt vmcnt(26)
	v_dot4c_i32_i8_e32 v68, v60, v170
	v_mov_b32_e32 v60, v177
	s_waitcnt vmcnt(25)
	v_dot4c_i32_i8_e32 v60, v56, v170
	v_mov_b32_e32 v56, v177
	s_waitcnt vmcnt(24)
	v_dot4c_i32_i8_e32 v56, v48, v170
	v_mov_b32_e32 v48, v177
	s_waitcnt vmcnt(23)
	v_dot4c_i32_i8_e32 v48, v44, v170
	v_mov_b32_e32 v44, v177
	s_waitcnt vmcnt(22)
	v_dot4c_i32_i8_e32 v44, v40, v170
	v_mov_b32_e32 v40, v177
	s_waitcnt vmcnt(21)
	v_dot4c_i32_i8_e32 v40, v36, v170
	v_mov_b32_e32 v36, v177
	s_waitcnt vmcnt(20)
	v_dot4c_i32_i8_e32 v36, v32, v170
	global_load_dwordx4 v[120:123], v214, s[14:15]
	v_mov_b32_e32 v32, v177
	s_waitcnt vmcnt(20)
	v_dot4c_i32_i8_e32 v32, v28, v170
	v_mov_b32_e32 v28, v177
	s_waitcnt vmcnt(19)
	v_dot4c_i32_i8_e32 v28, v24, v170
	v_mov_b32_e32 v24, v177
	s_waitcnt vmcnt(18)
	v_dot4c_i32_i8_e32 v24, v20, v170
	v_mov_b32_e32 v20, v177
	v_dot4c_i32_i8_e32 v80, v77, v171
	v_dot4c_i32_i8_e32 v60, v57, v171
	s_waitcnt vmcnt(17)
	v_dot4c_i32_i8_e32 v20, v12, v170
	v_dot4c_i32_i8_e32 v80, v78, v172
	v_dot4c_i32_i8_e32 v76, v73, v171
	v_dot4c_i32_i8_e32 v60, v58, v172
	v_dot4c_i32_i8_e32 v56, v49, v171
	v_dot4c_i32_i8_e32 v20, v13, v171
	v_dot4c_i32_i8_e32 v80, v79, v173
	global_load_dwordx4 v[108:111], v215, s[14:15]
	v_dot4c_i32_i8_e32 v76, v74, v172
	v_dot4c_i32_i8_e32 v72, v69, v171
	v_dot4c_i32_i8_e32 v60, v59, v173
	v_dot4c_i32_i8_e32 v56, v50, v172
	v_dot4c_i32_i8_e32 v48, v45, v171
	v_dot4c_i32_i8_e32 v20, v14, v172
	v_dot4c_i32_i8_e32 v76, v75, v173
	v_dot4c_i32_i8_e32 v72, v70, v172
	v_dot4c_i32_i8_e32 v68, v61, v171
	v_dot4c_i32_i8_e32 v56, v51, v173
	v_dot4c_i32_i8_e32 v48, v46, v172
	v_dot4c_i32_i8_e32 v44, v41, v171
	v_dot4c_i32_i8_e32 v24, v21, v171
	v_dot4c_i32_i8_e32 v20, v15, v173
	v_cndmask_b32_e64 v15, v80, v60, s[0:1]
	v_cndmask_b32_e64 v21, v60, v80, s[0:1]
	global_load_dwordx4 v[112:115], v216, s[14:15]
	v_dot4c_i32_i8_e32 v72, v71, v173
	v_dot4c_i32_i8_e32 v68, v62, v172
	v_dot4c_i32_i8_e32 v48, v47, v173
	v_dot4c_i32_i8_e32 v44, v42, v172
	v_dot4c_i32_i8_e32 v24, v22, v172
	v_add_u32_dpp v15, v21, v15 row_half_mirror row_mask:0xf bank_mask:0xf bound_ctrl:1
	v_cndmask_b32_e64 v21, v76, v56, s[0:1]
	v_cndmask_b32_e64 v22, v56, v76, s[0:1]
	v_dot4c_i32_i8_e32 v68, v63, v173
	v_dot4c_i32_i8_e32 v44, v43, v173
	v_dot4c_i32_i8_e32 v24, v23, v173
	v_add_u32_dpp v21, v22, v21 row_half_mirror row_mask:0xf bank_mask:0xf bound_ctrl:1
	v_cndmask_b32_e64 v22, v72, v48, s[0:1]
	v_cndmask_b32_e64 v23, v48, v72, s[0:1]
	v_dot4c_i32_i8_e32 v28, v25, v171
	global_load_dwordx4 v[100:103], v217, s[14:15]
	v_cndmask_b32_e64 v25, v44, v68, s[0:1]
	v_add_u32_dpp v22, v23, v22 row_half_mirror row_mask:0xf bank_mask:0xf bound_ctrl:1
	v_cndmask_b32_e64 v23, v68, v44, s[0:1]
	v_dot4c_i32_i8_e32 v40, v37, v171
	v_mov_b32_e32 v12, v177
	v_add_u32_dpp v23, v25, v23 row_half_mirror row_mask:0xf bank_mask:0xf bound_ctrl:1
	v_cndmask_b32_e64 v25, v22, v15, s[4:5]
	v_cndmask_b32_e64 v15, v15, v22, s[4:5]
	v_cndmask_b32_e64 v22, v23, v21, s[4:5]
	v_cndmask_b32_e64 v21, v21, v23, s[4:5]
	v_dot4c_i32_i8_e32 v40, v38, v172
	v_dot4c_i32_i8_e32 v36, v33, v171
	s_waitcnt vmcnt(19)
	v_dot4c_i32_i8_e32 v12, v52, v170
	v_mov_b32_e32 v13, v177
	v_add_u32_dpp v15, v15, v25 quad_perm:[2,3,0,1] row_mask:0xf bank_mask:0xf bound_ctrl:1
	v_add_u32_dpp v21, v21, v22 quad_perm:[2,3,0,1] row_mask:0xf bank_mask:0xf bound_ctrl:1
	global_load_dwordx4 v[104:107], v218, s[14:15]
	v_dot4c_i32_i8_e32 v40, v39, v173
	v_dot4c_i32_i8_e32 v36, v34, v172
	v_dot4c_i32_i8_e32 v32, v29, v171
	v_dot4c_i32_i8_e32 v12, v53, v171
	s_waitcnt vmcnt(19)
	v_dot4c_i32_i8_e32 v13, v64, v170
	v_cndmask_b32_e64 v22, v21, v15, s[6:7]
	v_cndmask_b32_e64 v15, v15, v21, s[6:7]
	v_dot4c_i32_i8_e32 v36, v35, v173
	v_dot4c_i32_i8_e32 v32, v30, v172
	v_dot4c_i32_i8_e32 v12, v54, v172
	v_dot4c_i32_i8_e32 v13, v65, v171
	v_add_u32_dpp v15, v15, v22 quad_perm:[1,0,3,2] row_mask:0xf bank_mask:0xf bound_ctrl:1
	v_cndmask_b32_e64 v21, v40, v24, s[0:1]
	v_cndmask_b32_e64 v22, v24, v40, s[0:1]
	v_dot4c_i32_i8_e32 v32, v31, v173
	global_load_dwordx4 v[92:95], v219, s[14:15]
	v_dot4c_i32_i8_e32 v28, v26, v172
	v_dot4c_i32_i8_e32 v12, v55, v173
	v_dot4c_i32_i8_e32 v13, v66, v172
	v_add_u32_dpp v21, v22, v21 row_half_mirror row_mask:0xf bank_mask:0xf bound_ctrl:1
	v_cndmask_b32_e64 v22, v36, v20, s[0:1]
	v_cndmask_b32_e64 v20, v20, v36, s[0:1]
	v_dot4c_i32_i8_e32 v28, v27, v173
	v_dot4c_i32_i8_e32 v13, v67, v173
	v_add_u32_dpp v20, v20, v22 row_half_mirror row_mask:0xf bank_mask:0xf bound_ctrl:1
	v_cndmask_b32_e64 v22, v32, v12, s[0:1]
	v_cndmask_b32_e64 v12, v12, v32, s[0:1]
	v_cvt_f32_i32_e32 v15, v15
	s_cmp_lt_i32 s21, 0x10200
	v_add_u32_dpp v12, v12, v22 row_half_mirror row_mask:0xf bank_mask:0xf bound_ctrl:1
	v_cndmask_b32_e64 v22, v28, v13, s[0:1]
	v_cndmask_b32_e64 v13, v13, v28, s[0:1]
	v_mul_f32_e32 v14, 0x3c010204, v161
	s_cselect_b32 s28, s21, s38
	global_load_dwordx4 v[96:99], v220, s[14:15]
	v_add_u32_dpp v13, v13, v22 row_half_mirror row_mask:0xf bank_mask:0xf bound_ctrl:1
	v_cndmask_b32_e64 v22, v12, v21, s[4:5]
	v_cndmask_b32_e64 v12, v21, v12, s[4:5]
	v_cndmask_b32_e64 v21, v13, v20, s[4:5]
	v_cndmask_b32_e64 v13, v20, v13, s[4:5]
	v_add_u32_dpp v12, v12, v22 quad_perm:[2,3,0,1] row_mask:0xf bank_mask:0xf bound_ctrl:1
	s_ashr_i32 s29, s28, 31
	v_add_u32_dpp v13, v13, v21 quad_perm:[2,3,0,1] row_mask:0xf bank_mask:0xf bound_ctrl:1
	v_cndmask_b32_e64 v20, v13, v12, s[6:7]
	v_cndmask_b32_e64 v12, v12, v13, s[6:7]
	v_mul_f32_e32 v13, v14, v15
	v_cvt_pk_bf16_f32 v13, v13, s0
	v_add_u32_dpp v12, v12, v20 quad_perm:[1,0,3,2] row_mask:0xf bank_mask:0xf bound_ctrl:1
	v_cvt_f32_i32_e32 v12, v12
	s_lshl_b64 s[36:37], s[28:29], 8
	s_lshl_b64 s[28:29], s[28:29], 11
	global_store_short v[168:169], v13, off
	v_mul_f32_e32 v12, v14, v12
	v_cvt_pk_bf16_f32 v12, v12, s0
	global_store_short v[168:169], v12, off offset:16
	v_lshlrev_b32_e32 v170, 16, v4
	global_load_dwordx4 v[88:91], v221, s[14:15]
	v_and_b32_e32 v172, 0xffff0000, v4
	v_and_b32_e32 v181, 0xffff0000, v0
	v_lshlrev_b32_e32 v171, 16, v5
	v_and_b32_e32 v161, 0xffff0000, v5
	v_lshlrev_b32_e32 v180, 16, v1
	v_and_b32_e32 v178, 0xffff0000, v1
	v_lshl_add_u64 v[0:1], v[162:163], 0, s[36:37]
	v_lshl_add_u64 v[4:5], v[164:165], 0, s[28:29]
	s_waitcnt vmcnt(20)
; #define PEER_META(T, IA, IB, HA, HB) do { const int _t = (T) < TTOK ? (T) : wslot; \
;     IA = *(const u32x4*)(W_IDX(p) + (size_t)_t * 128 + r * 16); IB = *(const u32x4*)(W_IDX(p) + (size_t)_t * 128 + r * 16 + 8); \
;     const u16* _hp = W_H(p) + (size_t)_t * DM + x * 128 + 16 * c; HA = *(const u32x4*)(_hp); HB = *(const u32x4*)(_hp + 8); } while (0)
; #define PEER_GATHER(TAB, IA, IB, RR) do { _Pragma("unroll") for (int g = 0; g < 16; ++g) { \
;     const unsigned _w = (g < 8 ? IA : IB)[(g >> 1) & 3]; RR[g] = *(const u32x4*)((TAB) + row_off(_w, c16, (g & 1) != 0)); } } while (0)
; DI void phase_peer_dots(const Params& p, int layer, int wave) {
;     ...
;     DOTS_QUANT(hAb, hBb);
;     PEER_META(t + 3 * nslot, iAb, iBb, hAb, hBb);
;     PEER_GATHER(ub, iAa, iBa, rrA);
	v_mad_u32_u16 v206, v156, v195, v160
	v_mad_u32_u16 v207, v156, v195, v160 op_sel:[1,0,0,0]
	v_mad_u32_u16 v208, v157, v195, v160
	v_mad_u32_u16 v209, v157, v195, v160 op_sel:[1,0,0,0]
	v_mad_u32_u16 v210, v158, v195, v160
	v_mad_u32_u16 v211, v158, v195, v160 op_sel:[1,0,0,0]
	v_mad_u32_u16 v212, v159, v195, v160
	v_mad_u32_u16 v213, v159, v195, v160 op_sel:[1,0,0,0]
	v_mad_u32_u16 v214, v152, v195, v160
	v_mad_u32_u16 v215, v152, v195, v160 op_sel:[1,0,0,0]
	v_mad_u32_u16 v216, v153, v195, v160
	v_mad_u32_u16 v217, v153, v195, v160 op_sel:[1,0,0,0]
	v_mad_u32_u16 v218, v154, v195, v160
	v_mad_u32_u16 v219, v154, v195, v160 op_sel:[1,0,0,0]
	v_mad_u32_u16 v220, v155, v195, v160
	v_mad_u32_u16 v221, v155, v195, v160 op_sel:[1,0,0,0]
	v_lshlrev_b32_e32 v174, 16, v6
	v_and_b32_e32 v176, 0xffff0000, v6
	v_lshlrev_b32_e32 v183, 16, v2
	v_and_b32_e32 v185, 0xffff0000, v2
	v_lshlrev_b32_e32 v175, 16, v7
	v_and_b32_e32 v173, 0xffff0000, v7
	v_lshlrev_b32_e32 v184, 16, v3
	global_load_dwordx4 v[76:79], v206, s[14:15]
	v_and_b32_e32 v182, 0xffff0000, v3
	global_load_dwordx4 v[80:83], v[0:1], off offset:16
	global_load_dwordx4 v[84:87], v[0:1], off
	s_nop 0
	global_load_dwordx4 v[0:3], v[4:5], off offset:16
	s_nop 0
	global_load_dwordx4 v[4:7], v[4:5], off
	s_nop 0
	s_nop 0
	s_nop 0
	s_nop 0
	v_max3_f32 v152, |v170|, 0, |v172|
	v_max3_f32 v152, v152, |v171|, |v161|
	v_max3_f32 v152, v152, |v174|, |v176|
	v_max3_f32 v152, v152, |v175|, |v173|
	v_max3_f32 v152, v152, |v179|, |v181|
	v_max3_f32 v152, v152, |v180|, |v178|
	v_max3_f32 v152, v152, |v183|, |v185|
	v_max3_f32 v152, v152, |v184|, |v182|
	s_add_i32 s84, s53, s13
	s_cmp_gt_i32 s84, 0x101ff
	v_mov_b32_dpp v153, v152 quad_perm:[1,0,3,2] row_mask:0xf bank_mask:0xf bound_ctrl:1
	v_max_f32_e32 v153, v153, v153
	v_max_f32_e32 v152, v152, v153
	s_nop 1
	v_mov_b32_dpp v153, v152 quad_perm:[2,3,0,1] row_mask:0xf bank_mask:0xf bound_ctrl:1
	v_max_f32_e32 v153, v153, v153
	global_load_dwordx4 v[72:75], v207, s[14:15]
	v_max_f32_e32 v152, v152, v153
	s_nop 1
	v_mov_b32_dpp v153, v152 row_half_mirror row_mask:0xf bank_mask:0xf bound_ctrl:1
	s_cbranch_scc1 .LBB0_129
	v_max_f32_e32 v153, v153, v153
	v_max_f32_e32 v152, v152, v152
	v_max_f32_e32 v152, v152, v153
	v_div_scale_f32 v153, s[28:29], v152, v152, s63
	v_rcp_f32_e32 v154, v153
	s_ashr_i32 s85, s84, 31
	s_lshl_b64 s[28:29], s[84:85], 11
	v_fma_f32 v155, -v153, v154, 1.0
	v_fmac_f32_e32 v154, v155, v154
	v_div_scale_f32 v155, vcc, s63, v152, s63
	v_mul_f32_e32 v156, v155, v154
	v_fma_f32 v157, -v153, v156, v155
	v_fmac_f32_e32 v156, v157, v154
	v_fma_f32 v153, -v153, v156, v155
	v_div_fmas_f32 v153, v153, v154, v156
	global_load_dwordx4 v[68:71], v208, s[14:15]
	v_div_fixup_f32 v153, v153, v152, s63
	v_cmp_lt_f32_e32 vcc, 0, v152
	v_mul_f32_e32 v152, 0x3c010204, v152
	s_nop 0
	v_cndmask_b32_e32 v153, 0, v153, vcc
	v_mul_f32_e32 v154, v153, v185
	v_rndne_f32_e32 v154, v154
	v_mul_f32_e32 v155, v153, v183
	v_mul_f32_e32 v156, v153, v184
	v_cvt_i32_f32_e32 v154, v154
	v_rndne_f32_e32 v155, v155
	v_rndne_f32_e32 v156, v156
	v_mul_f32_e32 v157, v153, v182
	v_cvt_i32_f32_e32 v155, v155
	v_cvt_i32_f32_sdwa v156, v156 dst_sel:WORD_1 dst_unused:UNUSED_PAD src0_sel:DWORD
	global_load_dwordx4 v[60:63], v209, s[14:15]
	v_rndne_f32_e32 v157, v157
	v_cvt_i32_f32_sdwa v157, v157 dst_sel:BYTE_3 dst_unused:UNUSED_PAD src0_sel:DWORD
	v_lshlrev_b32_e32 v154, 8, v154
	v_perm_b32 v154, v154, v155, s72
	v_and_b32_e32 v155, 0xff0000, v156
	v_or3_b32 v154, v154, v155, v157
	v_mul_f32_e32 v155, v153, v181
	v_rndne_f32_e32 v155, v155
	v_mul_f32_e32 v156, v153, v179
	v_mul_f32_e32 v157, v153, v180
	v_cvt_i32_f32_e32 v155, v155
	v_rndne_f32_e32 v156, v156
	v_rndne_f32_e32 v157, v157
	v_mul_f32_e32 v158, v153, v178
	v_cvt_i32_f32_e32 v156, v156
	global_load_dwordx4 v[56:59], v210, s[14:15]
	v_cvt_i32_f32_sdwa v157, v157 dst_sel:WORD_1 dst_unused:UNUSED_PAD src0_sel:DWORD
	v_rndne_f32_e32 v158, v158
	v_cvt_i32_f32_sdwa v158, v158 dst_sel:BYTE_3 dst_unused:UNUSED_PAD src0_sel:DWORD
	v_lshlrev_b32_e32 v155, 8, v155
	v_perm_b32 v155, v155, v156, s72
	v_and_b32_e32 v156, 0xff0000, v157
	v_or3_b32 v155, v155, v156, v158
	v_mul_f32_e32 v156, v153, v176
	v_rndne_f32_e32 v156, v156
	v_mul_f32_e32 v157, v153, v174
	v_mul_f32_e32 v158, v153, v175
	v_cvt_i32_f32_e32 v156, v156
	v_rndne_f32_e32 v157, v157
	v_rndne_f32_e32 v158, v158
	v_mul_f32_e32 v159, v153, v173
	global_load_dwordx4 v[48:51], v211, s[14:15]
	v_cvt_i32_f32_e32 v157, v157
	v_cvt_i32_f32_sdwa v158, v158 dst_sel:WORD_1 dst_unused:UNUSED_PAD src0_sel:DWORD
	v_rndne_f32_e32 v159, v159
	v_cvt_i32_f32_sdwa v159, v159 dst_sel:BYTE_3 dst_unused:UNUSED_PAD src0_sel:DWORD
	v_lshlrev_b32_e32 v156, 8, v156
	v_perm_b32 v156, v156, v157, s72
	v_and_b32_e32 v157, 0xff0000, v158
	v_or3_b32 v156, v156, v157, v159
	v_mul_f32_e32 v157, v153, v172
	v_rndne_f32_e32 v157, v157
	v_mul_f32_e32 v158, v153, v170
	v_mul_f32_e32 v159, v153, v171
	v_cvt_i32_f32_e32 v157, v157
	v_rndne_f32_e32 v158, v158
	global_load_dwordx4 v[44:47], v212, s[14:15]
	v_rndne_f32_e32 v159, v159
	v_mul_f32_e32 v153, v153, v161
	v_cvt_i32_f32_e32 v158, v158
	v_cvt_i32_f32_sdwa v159, v159 dst_sel:WORD_1 dst_unused:UNUSED_PAD src0_sel:DWORD
	v_rndne_f32_e32 v153, v153
	v_cvt_i32_f32_sdwa v153, v153 dst_sel:BYTE_3 dst_unused:UNUSED_PAD src0_sel:DWORD
	v_lshlrev_b32_e32 v157, 8, v157
	v_perm_b32 v157, v157, v158, s72
	v_and_b32_e32 v158, 0xff0000, v159
	v_or3_b32 v153, v157, v158, v153
	v_mov_b32_e32 v157, v177
	s_waitcnt vmcnt(30)
	v_dot4c_i32_i8_e32 v157, v148, v153
	v_mov_b32_e32 v148, v177
	s_waitcnt vmcnt(29)
; #define DPP_I(v, ctrl) __builtin_amdgcn_update_dpp(0, (v), (ctrl), 0xf, 0xf, true)
; DI int reduce_scatter8(int d0, int d1, int d2, int d3, int d4, int d5, int d6, int d7, int c) {
;   const bool b2 = c >= 4, b1 = (c & 2) != 0, b0 = (c & 1) != 0;
;   const int e0 = (b2 ? d4 : d0) + DPP_I(b2 ? d0 : d4, 0x141);
;   const int e1 = (b2 ? d5 : d1) + DPP_I(b2 ? d1 : d5, 0x141);
;   const int e2 = (b2 ? d6 : d2) + DPP_I(b2 ? d2 : d6, 0x141);
;   const int e3 = (b2 ? d7 : d3) + DPP_I(b2 ? d3 : d7, 0x141);
;   const int f0 = (b1 ? e2 : e0) + DPP_I(b1 ? e0 : e2, 0x4E);
;   const int f1 = (b1 ? e3 : e1) + DPP_I(b1 ? e1 : e3, 0x4E);
;   return (b0 ? f1 : f0) + DPP_I(b0 ? f0 : f1, 0xB1);
; }
	v_dot4c_i32_i8_e32 v148, v140, v153
	v_dot4c_i32_i8_e32 v148, v141, v156
	global_load_dwordx4 v[40:43], v213, s[14:15]
	v_mov_b32_e32 v141, v177
	s_waitcnt vmcnt(28)
	v_dot4c_i32_i8_e32 v141, v132, v153
	v_dot4c_i32_i8_e32 v141, v133, v156
	v_mov_b32_e32 v133, v177
	s_waitcnt vmcnt(26)
	v_dot4c_i32_i8_e32 v133, v124, v153
	v_dot4c_i32_i8_e32 v133, v125, v156
	v_mov_b32_e32 v125, v177
	s_waitcnt vmcnt(22)
	v_dot4c_i32_i8_e32 v125, v116, v153
	v_dot4c_i32_i8_e32 v125, v117, v156
	v_mov_b32_e32 v117, v177
	s_waitcnt vmcnt(20)
	v_dot4c_i32_i8_e32 v117, v108, v153
	v_dot4c_i32_i8_e32 v117, v109, v156
	v_mov_b32_e32 v109, v177
	v_mov_b32_e32 v132, v177
	global_load_dwordx4 v[36:39], v214, s[14:15]
	s_waitcnt vmcnt(19)
	v_dot4c_i32_i8_e32 v109, v100, v153
	v_dot4c_i32_i8_e32 v132, v136, v153
	v_dot4c_i32_i8_e32 v109, v101, v156
	v_mov_b32_e32 v101, v177
	v_dot4c_i32_i8_e32 v157, v149, v156
	v_mov_b32_e32 v140, v177
	v_dot4c_i32_i8_e32 v132, v137, v156
	v_mov_b32_e32 v124, v177
	s_waitcnt vmcnt(17)
	v_dot4c_i32_i8_e32 v101, v92, v153
	v_dot4c_i32_i8_e32 v157, v150, v155
	v_dot4c_i32_i8_e32 v140, v144, v153
	v_dot4c_i32_i8_e32 v132, v138, v155
	v_dot4c_i32_i8_e32 v124, v128, v153
	v_dot4c_i32_i8_e32 v101, v93, v156
	v_mov_b32_e32 v93, v177
	global_load_dwordx4 v[32:35], v215, s[14:15]
	v_dot4c_i32_i8_e32 v157, v151, v154
	v_dot4c_i32_i8_e32 v148, v142, v155
	v_dot4c_i32_i8_e32 v140, v145, v156
	v_dot4c_i32_i8_e32 v132, v139, v154
	v_dot4c_i32_i8_e32 v133, v126, v155
	v_dot4c_i32_i8_e32 v124, v129, v156
	s_waitcnt vmcnt(14)
	v_dot4c_i32_i8_e32 v93, v88, v153
	v_dot4c_i32_i8_e32 v148, v143, v154
	v_dot4c_i32_i8_e32 v140, v146, v155
	v_dot4c_i32_i8_e32 v133, v127, v154
	v_dot4c_i32_i8_e32 v124, v130, v155
	v_dot4c_i32_i8_e32 v93, v89, v156
	v_cndmask_b32_e64 v88, v157, v132, s[0:1]
	v_cndmask_b32_e64 v89, v132, v157, s[0:1]
	global_load_dwordx4 v[28:31], v216, s[14:15]
	v_dot4c_i32_i8_e32 v140, v147, v154
	v_dot4c_i32_i8_e32 v141, v134, v155
	v_dot4c_i32_i8_e32 v124, v131, v154
	v_dot4c_i32_i8_e32 v125, v118, v155
	v_dot4c_i32_i8_e32 v93, v90, v155
	v_add_u32_dpp v88, v89, v88 row_half_mirror row_mask:0xf bank_mask:0xf bound_ctrl:1
	v_cndmask_b32_e64 v89, v148, v133, s[0:1]
	v_cndmask_b32_e64 v90, v133, v148, s[0:1]
	v_dot4c_i32_i8_e32 v141, v135, v154
	v_dot4c_i32_i8_e32 v125, v119, v154
	v_dot4c_i32_i8_e32 v93, v91, v154
	v_add_u32_dpp v89, v90, v89 row_half_mirror row_mask:0xf bank_mask:0xf bound_ctrl:1
	v_cndmask_b32_e64 v90, v140, v124, s[0:1]
	v_cndmask_b32_e64 v91, v124, v140, s[0:1]
	v_mov_b32_e32 v116, v177
	global_load_dwordx4 v[24:27], v217, s[14:15]
	v_mov_b32_e32 v100, v177
	v_dot4c_i32_i8_e32 v101, v94, v155
	v_add_u32_dpp v90, v91, v90 row_half_mirror row_mask:0xf bank_mask:0xf bound_ctrl:1
	v_cndmask_b32_e64 v91, v141, v125, s[0:1]
	v_cndmask_b32_e64 v94, v125, v141, s[0:1]
	v_dot4c_i32_i8_e32 v116, v120, v153
	v_dot4c_i32_i8_e32 v100, v104, v153
	v_add_u32_dpp v91, v94, v91 row_half_mirror row_mask:0xf bank_mask:0xf bound_ctrl:1
	v_dot4c_i32_i8_e32 v116, v121, v156
	v_mov_b32_e32 v108, v177
	v_dot4c_i32_i8_e32 v100, v105, v156
	v_mov_b32_e32 v92, v177
	v_cndmask_b32_e64 v94, v90, v88, s[4:5]
	v_cndmask_b32_e64 v88, v88, v90, s[4:5]
	v_cndmask_b32_e64 v90, v91, v89, s[4:5]
	global_load_dwordx4 v[20:23], v218, s[14:15]
	v_cndmask_b32_e64 v89, v89, v91, s[4:5]
	v_dot4c_i32_i8_e32 v116, v122, v155
	v_dot4c_i32_i8_e32 v108, v112, v153
	v_dot4c_i32_i8_e32 v100, v106, v155
	v_dot4c_i32_i8_e32 v92, v96, v153
	v_add_u32_dpp v88, v88, v94 quad_perm:[2,3,0,1] row_mask:0xf bank_mask:0xf bound_ctrl:1
	v_add_u32_dpp v89, v89, v90 quad_perm:[2,3,0,1] row_mask:0xf bank_mask:0xf bound_ctrl:1
	v_dot4c_i32_i8_e32 v116, v123, v154
	v_dot4c_i32_i8_e32 v117, v110, v155
	v_dot4c_i32_i8_e32 v108, v113, v156
	v_dot4c_i32_i8_e32 v100, v107, v154
	v_dot4c_i32_i8_e32 v92, v97, v156
	v_cndmask_b32_e64 v90, v89, v88, s[6:7]
	v_cndmask_b32_e64 v88, v88, v89, s[6:7]
	global_load_dwordx4 v[12:15], v219, s[14:15]
	v_dot4c_i32_i8_e32 v117, v111, v154
	v_dot4c_i32_i8_e32 v108, v114, v155
	v_dot4c_i32_i8_e32 v101, v95, v154
	v_dot4c_i32_i8_e32 v92, v98, v155
	v_add_u32_dpp v88, v88, v90 quad_perm:[1,0,3,2] row_mask:0xf bank_mask:0xf bound_ctrl:1
	v_cndmask_b32_e64 v89, v116, v100, s[0:1]
	v_cndmask_b32_e64 v90, v100, v116, s[0:1]
	v_dot4c_i32_i8_e32 v108, v115, v154
	v_dot4c_i32_i8_e32 v109, v102, v155
	v_dot4c_i32_i8_e32 v92, v99, v154
	v_add_u32_dpp v89, v90, v89 row_half_mirror row_mask:0xf bank_mask:0xf bound_ctrl:1
	v_cndmask_b32_e64 v90, v117, v101, s[0:1]
	v_cndmask_b32_e64 v91, v101, v117, s[0:1]
	v_dot4c_i32_i8_e32 v109, v103, v154
	s_nop 0
	v_add_u32_dpp v90, v91, v90 row_half_mirror row_mask:0xf bank_mask:0xf bound_ctrl:1
	global_load_dwordx4 v[52:55], v220, s[14:15]
	v_cndmask_b32_e64 v91, v108, v92, s[0:1]
	v_cndmask_b32_e64 v92, v92, v108, s[0:1]
	s_nop 1
	v_add_u32_dpp v91, v92, v91 row_half_mirror row_mask:0xf bank_mask:0xf bound_ctrl:1
	v_cndmask_b32_e64 v92, v109, v93, s[0:1]
	v_cndmask_b32_e64 v93, v93, v109, s[0:1]
	s_nop 1
	v_add_u32_dpp v92, v93, v92 row_half_mirror row_mask:0xf bank_mask:0xf bound_ctrl:1
	v_cndmask_b32_e64 v93, v91, v89, s[4:5]
	v_cndmask_b32_e64 v89, v89, v91, s[4:5]
	v_cndmask_b32_e64 v91, v92, v90, s[4:5]
	v_cndmask_b32_e64 v90, v90, v92, s[4:5]
	v_add_u32_dpp v89, v89, v93 quad_perm:[2,3,0,1] row_mask:0xf bank_mask:0xf bound_ctrl:1
	s_nop 0
	v_add_u32_dpp v90, v90, v91 quad_perm:[2,3,0,1] row_mask:0xf bank_mask:0xf bound_ctrl:1
	v_cndmask_b32_e64 v91, v90, v89, s[6:7]
	v_cndmask_b32_e64 v89, v89, v90, s[6:7]
	s_nop 1
	global_load_dwordx4 v[64:67], v221, s[14:15]
	v_add_u32_dpp v90, v89, v91 quad_perm:[1,0,3,2] row_mask:0xf bank_mask:0xf bound_ctrl:1
	v_cvt_f32_i32_e32 v91, v88
	v_cvt_f32_i32_e32 v90, v90
	v_lshl_add_u64 v[88:89], v[166:167], 0, s[28:29]
	v_mul_f32_e32 v91, v152, v91
	v_mul_f32_e32 v90, v152, v90
	v_cvt_pk_bf16_f32 v91, v91, s0
	v_cvt_pk_bf16_f32 v90, v90, s0
	global_store_short v[88:89], v91, off
	global_store_short v[88:89], v90, off offset:16
	s_branch .LBB0_129

; DI int otid_w(int wave) { unsigned z = 0u; asm volatile("" : "+v"(z)); int t = wave * 64 + (int)__builtin_amdgcn_mbcnt_hi(~0u, __builtin_amdgcn_mbcnt_lo(~0u, z)); asm volatile("" : "+v"(t)); return t; }
; #define PEER_GATHER(TAB, IA, IB, RR) do { _Pragma("unroll") for (int g = 0; g < 16; ++g) { \
;     const unsigned _w = (g < 8 ? IA : IB)[(g >> 1) & 3]; RR[g] = *(const u32x4*)((TAB) + row_off(_w, c16, (g & 1) != 0)); } } while (0)
; DI void phase_peer_v(const Params& p, int layer, int wave) {
;   const int tid = otid_w(wave), lane = tid & 63, wid = wave, c = lane & 7, r = lane >> 3;
;   const int x = blockIdx.x & 7, wslot = (blockIdx.x >> 3) * 8 + wid, nslot = (gridDim.x >> 3) * 8;
;   const unsigned char* vb = W_VB(p) + (size_t)x * (PEER_N * 128);
;   const unsigned c16 = (unsigned)c * 16u;
;   u16* y2 = W_Y(p);
;   const int ocol = x * 128 + 16 * c + 4 * ((lane >> 4) & 1) + 8 * (lane >> 5);
;   u32x4 iAa, iBa, iAb, iBb;
;   u32x4 wAa, wBa, wAb, wBb, wA, wB;
;   u32x2 hRa, hRb, hR;
;   u32x4 rrA[16], rrB[16];
;     ...
;   int t = wslot;
;   PEER_META_V(t, iAa, iBa, wAa, wBa, hRa);
;   PEER_META_V(t + nslot, iAb, iBb, wAb, wBb, hRb);
;   PEER_GATHER(vb, iAa, iBa, rrA);
.LBB0_184:
	s_and_b64 vcc, exec, s[78:79]
	s_cbranch_vccz .LBB0_195
	s_waitcnt vmcnt(0)
	v_mov_b32_e32 v0, v177
	v_readlane_b32 s0, v253, 51
	v_mbcnt_lo_u32_b32 v0, -1, v0
	v_mbcnt_hi_u32_b32 v0, -1, v0
	v_add_u32_e32 v0, s64, v0
	v_readlane_b32 s1, v253, 52
	v_lshlrev_b32_e32 v1, 1, v0
	v_and_b32_e32 v1, 0x70, v1
	v_lshlrev_b32_e32 v176, 1, v1
	s_waitcnt lgkmcnt(0)
	s_nop 0
	global_load_dwordx4 v[6:9], v176, s[0:1]
	global_load_dwordx4 v[12:15], v176, s[0:1] offset:16
	v_readlane_b32 s0, v253, 56
	v_readlane_b32 s1, v253, 57
	v_lshlrev_b32_e32 v1, 4, v0
	s_andn2_b64 vcc, exec, s[0:1]
	v_and_b32_e32 v205, 0x70, v1
	s_waitcnt vmcnt(1)
	v_mad_u32_u16 v2, v6, v195, v205
	v_mad_u32_u16 v3, v6, v195, v205 op_sel:[1,0,0,0]
	v_mad_u32_u16 v4, v7, v195, v205
	v_mad_u32_u16 v5, v7, v195, v205 op_sel:[1,0,0,0]
	v_mad_u32_u16 v6, v8, v195, v205
	v_mad_u32_u16 v7, v8, v195, v205 op_sel:[1,0,0,0]
	v_mad_u32_u16 v8, v9, v195, v205
	v_mad_u32_u16 v9, v9, v195, v205 op_sel:[1,0,0,0]
	s_waitcnt vmcnt(0)
	v_mad_u32_u16 v10, v12, v195, v205
	v_mad_u32_u16 v11, v12, v195, v205 op_sel:[1,0,0,0]
	v_mad_u32_u16 v16, v13, v195, v205
	v_mad_u32_u16 v17, v13, v195, v205 op_sel:[1,0,0,0]
	v_mad_u32_u16 v18, v14, v195, v205
	v_mad_u32_u16 v19, v14, v195, v205 op_sel:[1,0,0,0]
	v_mad_u32_u16 v12, v15, v195, v205
	v_mad_u32_u16 v1, v15, v195, v205 op_sel:[1,0,0,0]
	s_cbranch_vccnz .LBB0_194
	v_lshrrev_b32_e32 v13, 2, v0
	v_and_b32_e32 v38, 12, v13
	v_readlane_b32 s4, v253, 53
	v_readlane_b32 s0, v254, 28
	v_readlane_b32 s1, v254, 29
	v_or3_b32 v13, v38, s4, v205
	v_lshlrev_b32_e32 v36, 1, v13
	global_load_dwordx4 v[12:15], v12, s[80:81]
	s_nop 0
	global_load_dwordx4 v[20:23], v19, s[80:81]
	global_load_dwordx4 v[24:27], v18, s[80:81]
	global_load_dwordx4 v[28:31], v17, s[80:81]
	global_load_dwordx4 v[32:35], v16, s[80:81]
	global_load_dwordx4 v[40:43], v11, s[80:81]
	global_load_dwordx4 v[52:55], v10, s[80:81]
	global_load_dwordx4 v[60:63], v9, s[80:81]
	global_load_dwordx4 v[68:71], v8, s[80:81]
	global_load_dwordx4 v[80:83], v7, s[80:81]
	global_load_dwordx4 v[88:91], v6, s[80:81]
	global_load_dwordx4 v[96:99], v5, s[80:81]
	global_load_dwordx4 v[104:107], v4, s[80:81]
	global_load_dwordx4 v[112:115], v3, s[80:81]
	global_load_dwordx4 v[120:123], v2, s[80:81]
	v_lshl_add_u64 v[180:181], s[0:1], 0, v[176:177]
	v_readlane_b32 s0, v253, 58
	v_readlane_b32 s1, v253, 59
	v_and_b32_e32 v0, 8, v0
	v_lshl_add_u64 v[178:179], s[66:67], 0, v[176:177]
	v_mov_b32_e32 v37, v177
	v_lshl_add_u64 v[182:183], s[76:77], 0, v[36:37]
	v_lshl_add_u64 v[184:185], s[50:51], 0, v[36:37]
	global_load_dwordx2 v[186:187], v36, s[0:1]
	v_readlane_b32 s0, v254, 26
	v_readlane_b32 s1, v254, 27
	s_nop 4
	global_load_dwordx4 v[8:11], v176, s[0:1] offset:16
	global_load_dwordx4 v[72:75], v176, s[0:1]
	v_readlane_b32 s0, v253, 62
	v_readlane_b32 s1, v253, 63
	s_nop 4
	global_load_dwordx4 v[128:131], v176, s[0:1] offset:16
	global_load_dwordx4 v[140:143], v176, s[0:1]
	v_readlane_b32 s0, v254, 0
	v_readlane_b32 s1, v254, 1
	s_mov_b32 s8, s38
	s_nop 3
	global_load_dwordx2 v[160:161], v36, s[0:1]
	v_readlane_b32 s0, v254, 30
	v_readlane_b32 s1, v254, 31
	s_nop 4
	global_load_dwordx4 v[168:171], v176, s[0:1] offset:16
	global_load_dwordx4 v[172:175], v176, s[0:1]
	global_load_dwordx4 v[16:19], v1, s[80:81]
	v_cmp_eq_u32_e64 s[0:1], 0, v0
	v_add_u32_e32 v0, s4, v205
	v_readlane_b32 s4, v255, 20
	v_add_lshl_u32 v176, v0, v38, 1
	v_readlane_b32 s5, v255, 21
	s_nop 1
	v_lshl_add_u64 v[188:189], s[4:5], 0, v[176:177]
	s_waitcnt vmcnt(0)
	s_branch .LBB0_189

; #define PEER_GATHER(TAB, IA, IB, RR) do { _Pragma("unroll") for (int g = 0; g < 16; ++g) { \
;     const unsigned _w = (g < 8 ? IA : IB)[(g >> 1) & 3]; RR[g] = *(const u32x4*)((TAB) + row_off(_w, c16, (g & 1) != 0)); } } while (0)
; DI void phase_peer_v(const Params& p, int layer, int wave) {
;     ...
;     wA = wAa; wB = wBa; hR = hRa;
;     PEER_META_V(t + 2 * nslot, iAa, iBa, wAa, wBa, hRa);
;     PEER_GATHER(vb, iAb, iBb, rrB);
.LBB0_189:
	s_add_i32 s10, s8, s88
	s_cmp_gt_i32 s10, 0x101ff
	s_cselect_b64 s[4:5], -1, 0
	s_cmp_lt_i32 s10, 0x10200
	s_cselect_b32 s6, s10, s38
	s_ashr_i32 s7, s6, 31
	s_lshl_b64 s[12:13], s[6:7], 8
	s_lshl_b64 s[6:7], s[6:7], 11
	v_lshl_add_u64 v[0:1], v[178:179], 0, s[12:13]
	v_lshl_add_u64 v[4:5], v[180:181], 0, s[12:13]
	v_lshl_add_u64 v[36:37], v[182:183], 0, s[6:7]
	global_load_dwordx4 v[152:155], v[0:1], off offset:16
	global_load_dwordx4 v[156:159], v[0:1], off
	s_nop 0
	global_load_dwordx4 v[0:3], v[4:5], off offset:16
	s_nop 0
	global_load_dwordx4 v[4:7], v[4:5], off
	global_load_dwordx2 v[190:191], v[36:37], off
	v_mad_u32_u16 v206, v140, v195, v205
	v_mad_u32_u16 v207, v140, v195, v205 op_sel:[1,0,0,0]
	v_mad_u32_u16 v208, v141, v195, v205
	v_mad_u32_u16 v209, v141, v195, v205 op_sel:[1,0,0,0]
	v_mad_u32_u16 v210, v142, v195, v205
	v_mad_u32_u16 v211, v142, v195, v205 op_sel:[1,0,0,0]
	v_mad_u32_u16 v212, v143, v195, v205
	v_mad_u32_u16 v213, v143, v195, v205 op_sel:[1,0,0,0]
	v_mad_u32_u16 v214, v128, v195, v205
	v_mad_u32_u16 v215, v128, v195, v205 op_sel:[1,0,0,0]
	v_mad_u32_u16 v216, v129, v195, v205
	v_mad_u32_u16 v217, v129, v195, v205 op_sel:[1,0,0,0]
	v_mad_u32_u16 v218, v130, v195, v205
	v_mad_u32_u16 v219, v130, v195, v205 op_sel:[1,0,0,0]
	v_mad_u32_u16 v220, v131, v195, v205
	v_mad_u32_u16 v221, v131, v195, v205 op_sel:[1,0,0,0]
	s_waitcnt vmcnt(21)
	global_load_dwordx4 v[148:151], v206, s[80:81]
	v_cvt_pk_f32_fp8_e32 v[162:163], v122
	v_cvt_pk_f32_fp8_e32 v[130:131], v120
	v_cvt_pk_f32_fp8_sdwa v[140:141], v120 src0_sel:WORD_1
	v_cvt_pk_f32_fp8_e32 v[142:143], v121
	v_cvt_pk_f32_fp8_sdwa v[120:121], v121 src0_sel:WORD_1
	v_cvt_pk_f32_fp8_sdwa v[164:165], v122 src0_sel:WORD_1
	v_cvt_pk_f32_fp8_e32 v[166:167], v123
	v_cvt_pk_f32_fp8_sdwa v[122:123], v123 src0_sel:WORD_1
	s_waitcnt vmcnt(21)
	global_load_dwordx4 v[144:147], v207, s[80:81]
	v_cvt_pk_f32_fp8_e32 v[192:193], v112
	v_lshlrev_b32_e32 v128, 16, v172
	v_pk_fma_f32 v[130:131], v[128:129], v[130:131], 0 op_sel_hi:[0,1,0]
	v_pk_fma_f32 v[140:141], v[128:129], v[140:141], 0 op_sel_hi:[0,1,0]
	v_pk_fma_f32 v[142:143], v[128:129], v[142:143], 0 op_sel_hi:[0,1,0]
	v_pk_fma_f32 v[120:121], v[128:129], v[120:121], 0 op_sel_hi:[0,1,0]
	v_pk_fma_f32 v[162:163], v[128:129], v[162:163], 0 op_sel_hi:[0,1,0]
	v_pk_fma_f32 v[164:165], v[128:129], v[164:165], 0 op_sel_hi:[0,1,0]
	v_pk_fma_f32 v[166:167], v[128:129], v[166:167], 0 op_sel_hi:[0,1,0]
	v_pk_fma_f32 v[122:123], v[128:129], v[122:123], 0 op_sel_hi:[0,1,0]
	v_and_b32_e32 v128, 0xffff0000, v172
	v_cvt_pk_f32_fp8_sdwa v[202:203], v112 src0_sel:WORD_1
	v_pk_fma_f32 v[130:131], v[128:129], v[192:193], v[130:131] op_sel_hi:[0,1,1]
	v_cvt_pk_f32_fp8_e32 v[192:193], v113
	v_cvt_pk_f32_fp8_sdwa v[112:113], v113 src0_sel:WORD_1
	v_pk_fma_f32 v[140:141], v[128:129], v[202:203], v[140:141] op_sel_hi:[0,1,1]
	v_pk_fma_f32 v[142:143], v[128:129], v[192:193], v[142:143] op_sel_hi:[0,1,1]
	v_pk_fma_f32 v[112:113], v[128:129], v[112:113], v[120:121] op_sel_hi:[0,1,1]
	v_cvt_pk_f32_fp8_e32 v[120:121], v114
	v_cvt_pk_f32_fp8_sdwa v[192:193], v114 src0_sel:WORD_1
	v_pk_fma_f32 v[120:121], v[128:129], v[120:121], v[162:163] op_sel_hi:[0,1,1]
	v_pk_fma_f32 v[162:163], v[128:129], v[192:193], v[164:165] op_sel_hi:[0,1,1]
	v_cvt_pk_f32_fp8_e32 v[164:165], v115
	v_cvt_pk_f32_fp8_sdwa v[114:115], v115 src0_sel:WORD_1
	v_pk_fma_f32 v[164:165], v[128:129], v[164:165], v[166:167] op_sel_hi:[0,1,1]
	v_pk_fma_f32 v[114:115], v[128:129], v[114:115], v[122:123] op_sel_hi:[0,1,1]
	s_waitcnt vmcnt(21)
	global_load_dwordx4 v[136:139], v208, s[80:81]
	v_cvt_pk_f32_fp8_e32 v[128:129], v104
	v_cvt_pk_f32_fp8_sdwa v[166:167], v104 src0_sel:WORD_1
	v_lshlrev_b32_e32 v122, 16, v173
	v_pk_fma_f32 v[128:129], v[122:123], v[128:129], v[130:131] op_sel_hi:[0,1,1]
	v_pk_fma_f32 v[130:131], v[122:123], v[166:167], v[140:141] op_sel_hi:[0,1,1]
	v_cvt_pk_f32_fp8_e32 v[140:141], v105
	v_cvt_pk_f32_fp8_sdwa v[104:105], v105 src0_sel:WORD_1
	v_pk_fma_f32 v[140:141], v[122:123], v[140:141], v[142:143] op_sel_hi:[0,1,1]
	v_pk_fma_f32 v[104:105], v[122:123], v[104:105], v[112:113] op_sel_hi:[0,1,1]
	v_cvt_pk_f32_fp8_e32 v[112:113], v106
	v_cvt_pk_f32_fp8_sdwa v[142:143], v106 src0_sel:WORD_1
	v_pk_fma_f32 v[112:113], v[122:123], v[112:113], v[120:121] op_sel_hi:[0,1,1]
	v_pk_fma_f32 v[120:121], v[122:123], v[142:143], v[162:163] op_sel_hi:[0,1,1]
	v_cvt_pk_f32_fp8_e32 v[142:143], v107
	v_cvt_pk_f32_fp8_sdwa v[106:107], v107 src0_sel:WORD_1
	s_waitcnt vmcnt(21)
	global_load_dwordx4 v[132:135], v209, s[80:81]
	v_cvt_pk_f32_fp8_sdwa v[162:163], v96 src0_sel:WORD_1
	v_pk_fma_f32 v[142:143], v[122:123], v[142:143], v[164:165] op_sel_hi:[0,1,1]
	v_pk_fma_f32 v[106:107], v[122:123], v[106:107], v[114:115] op_sel_hi:[0,1,1]
	v_cvt_pk_f32_fp8_e32 v[122:123], v96
	v_and_b32_e32 v114, 0xffff0000, v173
	v_pk_fma_f32 v[122:123], v[114:115], v[122:123], v[128:129] op_sel_hi:[0,1,1]
	v_pk_fma_f32 v[128:129], v[114:115], v[162:163], v[130:131] op_sel_hi:[0,1,1]
	v_cvt_pk_f32_fp8_e32 v[130:131], v97
	v_cvt_pk_f32_fp8_sdwa v[96:97], v97 src0_sel:WORD_1
	v_pk_fma_f32 v[130:131], v[114:115], v[130:131], v[140:141] op_sel_hi:[0,1,1]
	v_pk_fma_f32 v[96:97], v[114:115], v[96:97], v[104:105] op_sel_hi:[0,1,1]
	v_cvt_pk_f32_fp8_e32 v[104:105], v98
	v_cvt_pk_f32_fp8_sdwa v[140:141], v98 src0_sel:WORD_1
	v_pk_fma_f32 v[104:105], v[114:115], v[104:105], v[112:113] op_sel_hi:[0,1,1]
	v_pk_fma_f32 v[112:113], v[114:115], v[140:141], v[120:121] op_sel_hi:[0,1,1]
	v_cvt_pk_f32_fp8_e32 v[120:121], v99
	v_cvt_pk_f32_fp8_sdwa v[98:99], v99 src0_sel:WORD_1
	s_waitcnt vmcnt(21)
	global_load_dwordx4 v[124:127], v210, s[80:81]
	v_cvt_pk_f32_fp8_sdwa v[140:141], v88 src0_sel:WORD_1
	v_pk_fma_f32 v[120:121], v[114:115], v[120:121], v[142:143] op_sel_hi:[0,1,1]
	v_pk_fma_f32 v[98:99], v[114:115], v[98:99], v[106:107] op_sel_hi:[0,1,1]
	v_cvt_pk_f32_fp8_e32 v[114:115], v88
	v_lshlrev_b32_e32 v106, 16, v174
	v_pk_fma_f32 v[114:115], v[106:107], v[114:115], v[122:123] op_sel_hi:[0,1,1]
	v_pk_fma_f32 v[122:123], v[106:107], v[140:141], v[128:129] op_sel_hi:[0,1,1]
	v_cvt_pk_f32_fp8_e32 v[128:129], v89
	v_cvt_pk_f32_fp8_sdwa v[88:89], v89 src0_sel:WORD_1
	v_pk_fma_f32 v[128:129], v[106:107], v[128:129], v[130:131] op_sel_hi:[0,1,1]
	v_pk_fma_f32 v[88:89], v[106:107], v[88:89], v[96:97] op_sel_hi:[0,1,1]
	v_cvt_pk_f32_fp8_e32 v[96:97], v90
	v_cvt_pk_f32_fp8_sdwa v[130:131], v90 src0_sel:WORD_1
	v_pk_fma_f32 v[96:97], v[106:107], v[96:97], v[104:105] op_sel_hi:[0,1,1]
	v_pk_fma_f32 v[104:105], v[106:107], v[130:131], v[112:113] op_sel_hi:[0,1,1]
	v_cvt_pk_f32_fp8_e32 v[112:113], v91
	v_cvt_pk_f32_fp8_sdwa v[90:91], v91 src0_sel:WORD_1
	v_pk_fma_f32 v[112:113], v[106:107], v[112:113], v[120:121] op_sel_hi:[0,1,1]
	v_pk_fma_f32 v[90:91], v[106:107], v[90:91], v[98:99] op_sel_hi:[0,1,1]
	s_waitcnt vmcnt(21)
	global_load_dwordx4 v[116:119], v211, s[80:81]
	v_cvt_pk_f32_fp8_e32 v[106:107], v80
	v_cvt_pk_f32_fp8_sdwa v[120:121], v80 src0_sel:WORD_1
	v_and_b32_e32 v98, 0xffff0000, v174
	v_pk_fma_f32 v[106:107], v[98:99], v[106:107], v[114:115] op_sel_hi:[0,1,1]
	v_pk_fma_f32 v[114:115], v[98:99], v[120:121], v[122:123] op_sel_hi:[0,1,1]
	v_cvt_pk_f32_fp8_e32 v[120:121], v81
	v_cvt_pk_f32_fp8_sdwa v[80:81], v81 src0_sel:WORD_1
	v_cvt_pk_f32_fp8_sdwa v[122:123], v82 src0_sel:WORD_1
	v_pk_fma_f32 v[120:121], v[98:99], v[120:121], v[128:129] op_sel_hi:[0,1,1]
	v_pk_fma_f32 v[80:81], v[98:99], v[80:81], v[88:89] op_sel_hi:[0,1,1]
	v_cvt_pk_f32_fp8_e32 v[88:89], v82
	v_pk_fma_f32 v[88:89], v[98:99], v[88:89], v[96:97] op_sel_hi:[0,1,1]
	v_pk_fma_f32 v[96:97], v[98:99], v[122:123], v[104:105] op_sel_hi:[0,1,1]
	v_cvt_pk_f32_fp8_e32 v[104:105], v83
	v_cvt_pk_f32_fp8_sdwa v[82:83], v83 src0_sel:WORD_1
	v_pk_fma_f32 v[104:105], v[98:99], v[104:105], v[112:113] op_sel_hi:[0,1,1]
	v_pk_fma_f32 v[82:83], v[98:99], v[82:83], v[90:91] op_sel_hi:[0,1,1]
	s_waitcnt vmcnt(21)
	global_load_dwordx4 v[108:111], v212, s[80:81]
	v_cvt_pk_f32_fp8_e32 v[98:99], v68
	v_cvt_pk_f32_fp8_sdwa v[112:113], v68 src0_sel:WORD_1
	v_lshlrev_b32_e32 v90, 16, v175
	v_pk_fma_f32 v[98:99], v[90:91], v[98:99], v[106:107] op_sel_hi:[0,1,1]
	v_pk_fma_f32 v[106:107], v[90:91], v[112:113], v[114:115] op_sel_hi:[0,1,1]
	v_cvt_pk_f32_fp8_e32 v[112:113], v69
	v_cvt_pk_f32_fp8_sdwa v[68:69], v69 src0_sel:WORD_1
	v_cvt_pk_f32_fp8_sdwa v[114:115], v70 src0_sel:WORD_1
	v_pk_fma_f32 v[112:113], v[90:91], v[112:113], v[120:121] op_sel_hi:[0,1,1]
	v_pk_fma_f32 v[68:69], v[90:91], v[68:69], v[80:81] op_sel_hi:[0,1,1]
	v_cvt_pk_f32_fp8_e32 v[80:81], v70
	v_pk_fma_f32 v[80:81], v[90:91], v[80:81], v[88:89] op_sel_hi:[0,1,1]
	v_pk_fma_f32 v[88:89], v[90:91], v[114:115], v[96:97] op_sel_hi:[0,1,1]
	v_cvt_pk_f32_fp8_e32 v[96:97], v71
	v_cvt_pk_f32_fp8_sdwa v[70:71], v71 src0_sel:WORD_1
	v_pk_fma_f32 v[96:97], v[90:91], v[96:97], v[104:105] op_sel_hi:[0,1,1]
	v_pk_fma_f32 v[70:71], v[90:91], v[70:71], v[82:83] op_sel_hi:[0,1,1]
	s_waitcnt vmcnt(21)
	global_load_dwordx4 v[100:103], v213, s[80:81]
	v_cvt_pk_f32_fp8_e32 v[90:91], v60
	v_cvt_pk_f32_fp8_sdwa v[104:105], v60 src0_sel:WORD_1
	v_and_b32_e32 v82, 0xffff0000, v175
	v_pk_fma_f32 v[90:91], v[82:83], v[90:91], v[98:99] op_sel_hi:[0,1,1]
	v_pk_fma_f32 v[98:99], v[82:83], v[104:105], v[106:107] op_sel_hi:[0,1,1]
	v_cvt_pk_f32_fp8_e32 v[104:105], v61
	v_cvt_pk_f32_fp8_sdwa v[60:61], v61 src0_sel:WORD_1
	v_cvt_pk_f32_fp8_sdwa v[106:107], v62 src0_sel:WORD_1
	v_pk_fma_f32 v[104:105], v[82:83], v[104:105], v[112:113] op_sel_hi:[0,1,1]
	v_pk_fma_f32 v[60:61], v[82:83], v[60:61], v[68:69] op_sel_hi:[0,1,1]
	v_cvt_pk_f32_fp8_e32 v[68:69], v62
	v_pk_fma_f32 v[68:69], v[82:83], v[68:69], v[80:81] op_sel_hi:[0,1,1]
	v_pk_fma_f32 v[80:81], v[82:83], v[106:107], v[88:89] op_sel_hi:[0,1,1]
	v_cvt_pk_f32_fp8_e32 v[88:89], v63
	v_cvt_pk_f32_fp8_sdwa v[62:63], v63 src0_sel:WORD_1
	v_pk_fma_f32 v[88:89], v[82:83], v[88:89], v[96:97] op_sel_hi:[0,1,1]
	v_pk_fma_f32 v[62:63], v[82:83], v[62:63], v[70:71] op_sel_hi:[0,1,1]
	s_waitcnt vmcnt(21)
	global_load_dwordx4 v[92:95], v214, s[80:81]
	v_cvt_pk_f32_fp8_e32 v[82:83], v52
	v_cvt_pk_f32_fp8_sdwa v[96:97], v52 src0_sel:WORD_1
	v_lshlrev_b32_e32 v70, 16, v168
	v_pk_fma_f32 v[82:83], v[70:71], v[82:83], v[90:91] op_sel_hi:[0,1,1]
	v_pk_fma_f32 v[90:91], v[70:71], v[96:97], v[98:99] op_sel_hi:[0,1,1]
	v_cvt_pk_f32_fp8_e32 v[96:97], v53
	v_cvt_pk_f32_fp8_sdwa v[52:53], v53 src0_sel:WORD_1
	v_cvt_pk_f32_fp8_sdwa v[98:99], v54 src0_sel:WORD_1
	v_pk_fma_f32 v[96:97], v[70:71], v[96:97], v[104:105] op_sel_hi:[0,1,1]
	v_pk_fma_f32 v[52:53], v[70:71], v[52:53], v[60:61] op_sel_hi:[0,1,1]
	v_cvt_pk_f32_fp8_e32 v[60:61], v54
	v_pk_fma_f32 v[60:61], v[70:71], v[60:61], v[68:69] op_sel_hi:[0,1,1]
	v_pk_fma_f32 v[68:69], v[70:71], v[98:99], v[80:81] op_sel_hi:[0,1,1]
	v_cvt_pk_f32_fp8_e32 v[80:81], v55
	v_cvt_pk_f32_fp8_sdwa v[54:55], v55 src0_sel:WORD_1
	v_pk_fma_f32 v[80:81], v[70:71], v[80:81], v[88:89] op_sel_hi:[0,1,1]
	v_pk_fma_f32 v[54:55], v[70:71], v[54:55], v[62:63] op_sel_hi:[0,1,1]
	s_waitcnt vmcnt(21)
	global_load_dwordx4 v[84:87], v215, s[80:81]
	v_cvt_pk_f32_fp8_e32 v[70:71], v40
	v_cvt_pk_f32_fp8_sdwa v[88:89], v40 src0_sel:WORD_1
	v_and_b32_e32 v62, 0xffff0000, v168
	v_pk_fma_f32 v[70:71], v[62:63], v[70:71], v[82:83] op_sel_hi:[0,1,1]
	v_pk_fma_f32 v[82:83], v[62:63], v[88:89], v[90:91] op_sel_hi:[0,1,1]
	v_cvt_pk_f32_fp8_e32 v[88:89], v41
	v_cvt_pk_f32_fp8_sdwa v[40:41], v41 src0_sel:WORD_1
	v_cvt_pk_f32_fp8_sdwa v[90:91], v42 src0_sel:WORD_1
	v_pk_fma_f32 v[88:89], v[62:63], v[88:89], v[96:97] op_sel_hi:[0,1,1]
	v_pk_fma_f32 v[40:41], v[62:63], v[40:41], v[52:53] op_sel_hi:[0,1,1]
	v_cvt_pk_f32_fp8_e32 v[52:53], v42
	v_pk_fma_f32 v[52:53], v[62:63], v[52:53], v[60:61] op_sel_hi:[0,1,1]
	v_pk_fma_f32 v[60:61], v[62:63], v[90:91], v[68:69] op_sel_hi:[0,1,1]
	v_cvt_pk_f32_fp8_e32 v[68:69], v43
	v_cvt_pk_f32_fp8_sdwa v[42:43], v43 src0_sel:WORD_1
	v_pk_fma_f32 v[68:69], v[62:63], v[68:69], v[80:81] op_sel_hi:[0,1,1]
	v_pk_fma_f32 v[42:43], v[62:63], v[42:43], v[54:55] op_sel_hi:[0,1,1]
	s_waitcnt vmcnt(21)
	global_load_dwordx4 v[76:79], v216, s[80:81]
	v_cvt_pk_f32_fp8_e32 v[62:63], v32
	v_cvt_pk_f32_fp8_sdwa v[80:81], v32 src0_sel:WORD_1
	v_lshlrev_b32_e32 v54, 16, v169
	v_pk_fma_f32 v[62:63], v[54:55], v[62:63], v[70:71] op_sel_hi:[0,1,1]
	v_pk_fma_f32 v[70:71], v[54:55], v[80:81], v[82:83] op_sel_hi:[0,1,1]
	v_cvt_pk_f32_fp8_e32 v[80:81], v33
	v_cvt_pk_f32_fp8_sdwa v[32:33], v33 src0_sel:WORD_1
	v_cvt_pk_f32_fp8_sdwa v[82:83], v34 src0_sel:WORD_1
	v_pk_fma_f32 v[80:81], v[54:55], v[80:81], v[88:89] op_sel_hi:[0,1,1]
	v_pk_fma_f32 v[32:33], v[54:55], v[32:33], v[40:41] op_sel_hi:[0,1,1]
	v_cvt_pk_f32_fp8_e32 v[40:41], v34
	v_pk_fma_f32 v[40:41], v[54:55], v[40:41], v[52:53] op_sel_hi:[0,1,1]
	v_pk_fma_f32 v[52:53], v[54:55], v[82:83], v[60:61] op_sel_hi:[0,1,1]
	v_cvt_pk_f32_fp8_e32 v[60:61], v35
	v_cvt_pk_f32_fp8_sdwa v[34:35], v35 src0_sel:WORD_1
	v_pk_fma_f32 v[60:61], v[54:55], v[60:61], v[68:69] op_sel_hi:[0,1,1]
	v_pk_fma_f32 v[34:35], v[54:55], v[34:35], v[42:43] op_sel_hi:[0,1,1]
	s_waitcnt vmcnt(21)
	global_load_dwordx4 v[64:67], v217, s[80:81]
	v_cvt_pk_f32_fp8_e32 v[54:55], v28
	v_cvt_pk_f32_fp8_sdwa v[68:69], v28 src0_sel:WORD_1
	v_and_b32_e32 v42, 0xffff0000, v169
	v_pk_fma_f32 v[54:55], v[42:43], v[54:55], v[62:63] op_sel_hi:[0,1,1]
	v_pk_fma_f32 v[62:63], v[42:43], v[68:69], v[70:71] op_sel_hi:[0,1,1]
	v_cvt_pk_f32_fp8_e32 v[68:69], v29
	v_cvt_pk_f32_fp8_sdwa v[28:29], v29 src0_sel:WORD_1
	v_cvt_pk_f32_fp8_sdwa v[70:71], v30 src0_sel:WORD_1
	v_pk_fma_f32 v[68:69], v[42:43], v[68:69], v[80:81] op_sel_hi:[0,1,1]
	v_pk_fma_f32 v[28:29], v[42:43], v[28:29], v[32:33] op_sel_hi:[0,1,1]
	v_cvt_pk_f32_fp8_e32 v[32:33], v30
	v_pk_fma_f32 v[32:33], v[42:43], v[32:33], v[40:41] op_sel_hi:[0,1,1]
	v_pk_fma_f32 v[40:41], v[42:43], v[70:71], v[52:53] op_sel_hi:[0,1,1]
	v_cvt_pk_f32_fp8_e32 v[52:53], v31
	v_cvt_pk_f32_fp8_sdwa v[30:31], v31 src0_sel:WORD_1
	v_pk_fma_f32 v[52:53], v[42:43], v[52:53], v[60:61] op_sel_hi:[0,1,1]
	v_pk_fma_f32 v[30:31], v[42:43], v[30:31], v[34:35] op_sel_hi:[0,1,1]
	s_waitcnt vmcnt(21)
	global_load_dwordx4 v[56:59], v218, s[80:81]
	v_cvt_pk_f32_fp8_e32 v[42:43], v24
	v_cvt_pk_f32_fp8_sdwa v[60:61], v24 src0_sel:WORD_1
	v_lshlrev_b32_e32 v34, 16, v170
	v_pk_fma_f32 v[42:43], v[34:35], v[42:43], v[54:55] op_sel_hi:[0,1,1]
	v_pk_fma_f32 v[54:55], v[34:35], v[60:61], v[62:63] op_sel_hi:[0,1,1]
	v_cvt_pk_f32_fp8_e32 v[60:61], v25
	v_cvt_pk_f32_fp8_sdwa v[24:25], v25 src0_sel:WORD_1
	v_cvt_pk_f32_fp8_sdwa v[62:63], v26 src0_sel:WORD_1
	v_pk_fma_f32 v[60:61], v[34:35], v[60:61], v[68:69] op_sel_hi:[0,1,1]
	v_pk_fma_f32 v[24:25], v[34:35], v[24:25], v[28:29] op_sel_hi:[0,1,1]
	v_cvt_pk_f32_fp8_e32 v[28:29], v26
	v_pk_fma_f32 v[28:29], v[34:35], v[28:29], v[32:33] op_sel_hi:[0,1,1]
	v_pk_fma_f32 v[32:33], v[34:35], v[62:63], v[40:41] op_sel_hi:[0,1,1]
	v_cvt_pk_f32_fp8_e32 v[40:41], v27
	v_cvt_pk_f32_fp8_sdwa v[26:27], v27 src0_sel:WORD_1
	v_pk_fma_f32 v[40:41], v[34:35], v[40:41], v[52:53] op_sel_hi:[0,1,1]
	v_pk_fma_f32 v[26:27], v[34:35], v[26:27], v[30:31] op_sel_hi:[0,1,1]
	s_waitcnt vmcnt(21)
	global_load_dwordx4 v[48:51], v219, s[80:81]
	v_cvt_pk_f32_fp8_e32 v[34:35], v20
	v_cvt_pk_f32_fp8_sdwa v[52:53], v20 src0_sel:WORD_1
	v_and_b32_e32 v30, 0xffff0000, v170
	v_pk_fma_f32 v[34:35], v[30:31], v[34:35], v[42:43] op_sel_hi:[0,1,1]
	v_pk_fma_f32 v[42:43], v[30:31], v[52:53], v[54:55] op_sel_hi:[0,1,1]
	v_cvt_pk_f32_fp8_e32 v[52:53], v21
	v_cvt_pk_f32_fp8_sdwa v[20:21], v21 src0_sel:WORD_1
	v_cvt_pk_f32_fp8_sdwa v[54:55], v22 src0_sel:WORD_1
	v_pk_fma_f32 v[52:53], v[30:31], v[52:53], v[60:61] op_sel_hi:[0,1,1]
	v_pk_fma_f32 v[20:21], v[30:31], v[20:21], v[24:25] op_sel_hi:[0,1,1]
	v_cvt_pk_f32_fp8_e32 v[24:25], v22
	v_pk_fma_f32 v[24:25], v[30:31], v[24:25], v[28:29] op_sel_hi:[0,1,1]
	v_pk_fma_f32 v[28:29], v[30:31], v[54:55], v[32:33] op_sel_hi:[0,1,1]
	v_cvt_pk_f32_fp8_e32 v[32:33], v23
	v_cvt_pk_f32_fp8_sdwa v[22:23], v23 src0_sel:WORD_1
	v_pk_fma_f32 v[32:33], v[30:31], v[32:33], v[40:41] op_sel_hi:[0,1,1]
	v_pk_fma_f32 v[22:23], v[30:31], v[22:23], v[26:27] op_sel_hi:[0,1,1]
	s_waitcnt vmcnt(21)
; #define PEER_GATHER(TAB, IA, IB, RR) do { _Pragma("unroll") for (int g = 0; g < 16; ++g) { \
;     const unsigned _w = (g < 8 ? IA : IB)[(g >> 1) & 3]; RR[g] = *(const u32x4*)((TAB) + row_off(_w, c16, (g & 1) != 0)); } } while (0)
; DI void phase_peer_v(const Params& p, int layer, int wave) {
;     ...
;   int t = wslot;
;   PEER_META_V(t, iAa, iBa, wAa, wBa, hRa);
;   PEER_META_V(t + nslot, iAb, iBb, wAb, wBb, hRb);
;   PEER_GATHER(vb, iAa, iBa, rrA);
;   for (; t < TTOK; t += 2 * nslot) {
;     wA = wAa; wB = wBa; hR = hRa;
;     PEER_META_V(t + 2 * nslot, iAa, iBa, wAa, wBa, hRa);
;     PEER_GATHER(vb, iAb, iBb, rrB);
;     V_COMPUTE(t, rrA);
;     wA = wAb; wB = wBb; hR = hRb;
;     PEER_META_V(t + 3 * nslot, iAb, iBb, wAb, wBb, hRb);
;     PEER_GATHER(vb, iAa, iBa, rrA);
	global_load_dwordx4 v[44:47], v220, s[80:81]
	v_cvt_pk_f32_fp8_e32 v[30:31], v12
	v_cvt_pk_f32_fp8_sdwa v[40:41], v12 src0_sel:WORD_1
	v_lshlrev_b32_e32 v26, 16, v171
	v_pk_fma_f32 v[30:31], v[26:27], v[30:31], v[34:35] op_sel_hi:[0,1,1]
	v_pk_fma_f32 v[34:35], v[26:27], v[40:41], v[42:43] op_sel_hi:[0,1,1]
	v_cvt_pk_f32_fp8_e32 v[40:41], v13
	v_cvt_pk_f32_fp8_sdwa v[12:13], v13 src0_sel:WORD_1
	v_cvt_pk_f32_fp8_sdwa v[42:43], v14 src0_sel:WORD_1
	v_pk_fma_f32 v[40:41], v[26:27], v[40:41], v[52:53] op_sel_hi:[0,1,1]
	v_pk_fma_f32 v[12:13], v[26:27], v[12:13], v[20:21] op_sel_hi:[0,1,1]
	v_cvt_pk_f32_fp8_e32 v[20:21], v14
	v_pk_fma_f32 v[20:21], v[26:27], v[20:21], v[24:25] op_sel_hi:[0,1,1]
	v_pk_fma_f32 v[24:25], v[26:27], v[42:43], v[28:29] op_sel_hi:[0,1,1]
	v_cvt_pk_f32_fp8_e32 v[28:29], v15
	v_cvt_pk_f32_fp8_sdwa v[14:15], v15 src0_sel:WORD_1
	v_pk_fma_f32 v[28:29], v[26:27], v[28:29], v[32:33] op_sel_hi:[0,1,1]
	v_pk_fma_f32 v[14:15], v[26:27], v[14:15], v[22:23] op_sel_hi:[0,1,1]
	s_waitcnt vmcnt(21)
	global_load_dwordx4 v[36:39], v221, s[80:81]
	v_cvt_pk_f32_fp8_e32 v[26:27], v16
	v_cvt_pk_f32_fp8_sdwa v[32:33], v16 src0_sel:WORD_1
	v_and_b32_e32 v22, 0xffff0000, v171
	v_pk_fma_f32 v[26:27], v[22:23], v[26:27], v[30:31] op_sel_hi:[0,1,1]
	v_pk_fma_f32 v[30:31], v[22:23], v[32:33], v[34:35] op_sel_hi:[0,1,1]
	v_cvt_pk_f32_fp8_e32 v[32:33], v17
	v_cvt_pk_f32_fp8_sdwa v[16:17], v17 src0_sel:WORD_1
	v_cvt_pk_f32_fp8_sdwa v[34:35], v18 src0_sel:WORD_1
	v_pk_fma_f32 v[32:33], v[22:23], v[32:33], v[40:41] op_sel_hi:[0,1,1]
	v_pk_fma_f32 v[12:13], v[22:23], v[16:17], v[12:13] op_sel_hi:[0,1,1]
	v_cvt_pk_f32_fp8_e32 v[16:17], v18
	v_pk_fma_f32 v[16:17], v[22:23], v[16:17], v[20:21] op_sel_hi:[0,1,1]
	v_pk_fma_f32 v[20:21], v[22:23], v[34:35], v[24:25] op_sel_hi:[0,1,1]
	v_cvt_pk_f32_fp8_e32 v[24:25], v19
	v_cvt_pk_f32_fp8_sdwa v[18:19], v19 src0_sel:WORD_1
	v_permlane32_swap_b32_e32 v26, v16
	v_pk_fma_f32 v[24:25], v[22:23], v[24:25], v[28:29] op_sel_hi:[0,1,1]
	v_pk_fma_f32 v[14:15], v[22:23], v[18:19], v[14:15] op_sel_hi:[0,1,1]
	v_permlane32_swap_b32_e32 v27, v17
	v_permlane32_swap_b32_e32 v30, v20
	v_permlane32_swap_b32_e32 v31, v21
	v_permlane32_swap_b32_e32 v32, v24
	v_permlane32_swap_b32_e32 v33, v25
	v_permlane32_swap_b32_e32 v12, v14
	v_permlane32_swap_b32_e32 v13, v15
	v_add_f32_e32 v16, v26, v16
	v_add_f32_e32 v17, v27, v17
	v_add_f32_e32 v18, v30, v20
	v_add_f32_e32 v19, v31, v21
	v_add_f32_e32 v20, v32, v24
	v_add_f32_e32 v21, v33, v25
	v_add_f32_e32 v14, v12, v14
	v_add_f32_e32 v15, v13, v15
	v_permlane16_swap_b32_e32 v16, v20
	v_permlane16_swap_b32_e32 v17, v21
	v_permlane16_swap_b32_e32 v18, v14
	v_permlane16_swap_b32_e32 v19, v15
	v_pk_add_f32 v[12:13], v[16:17], v[20:21]
	v_pk_add_f32 v[14:15], v[18:19], v[14:15]
	s_nop 0
	v_mov_b32_dpp v18, v12 row_ror:8 row_mask:0xf bank_mask:0xf bound_ctrl:1
	v_mov_b32_dpp v19, v13 row_ror:8 row_mask:0xf bank_mask:0xf bound_ctrl:1
	v_mov_b32_dpp v16, v14 row_ror:8 row_mask:0xf bank_mask:0xf bound_ctrl:1
	v_mov_b32_dpp v17, v15 row_ror:8 row_mask:0xf bank_mask:0xf bound_ctrl:1
	s_and_saveexec_b64 s[6:7], s[0:1]
	s_cbranch_execz .LBB0_191
	v_pk_add_f32 v[12:13], v[12:13], v[18:19]
	v_lshlrev_b32_e32 v18, 16, v160
	v_and_b32_e32 v19, 0xffff0000, v160
	v_pk_add_f32 v[14:15], v[14:15], v[16:17]
	v_lshlrev_b32_e32 v16, 16, v161
	v_and_b32_e32 v17, 0xffff0000, v161
	v_pk_fma_f32 v[12:13], v[18:19], s[86:87], v[12:13] op_sel_hi:[1,0,1]
	v_pk_fma_f32 v[14:15], v[16:17], s[86:87], v[14:15] op_sel_hi:[1,0,1]
	v_cvt_pk_bf16_f32 v12, v12, v13
	v_cvt_pk_bf16_f32 v13, v14, v15
	global_store_dwordx2 v[188:189], v[12:13], off
.LBB0_191:
	s_or_b64 exec, exec, s[6:7]
	s_add_i32 s6, s41, s8
	s_cmp_lt_i32 s6, 0x10200
	s_cselect_b32 s6, s6, s38
	s_ashr_i32 s7, s6, 31
	s_lshl_b64 s[12:13], s[6:7], 8
	v_lshl_add_u64 v[12:13], v[178:179], 0, s[12:13]
	global_load_dwordx4 v[128:131], v[12:13], off offset:16
	global_load_dwordx4 v[140:143], v[12:13], off
	v_lshl_add_u64 v[12:13], v[180:181], 0, s[12:13]
	s_lshl_b64 s[6:7], s[6:7], 11
	global_load_dwordx4 v[160:163], v[12:13], off offset:16
	global_load_dwordx4 v[164:167], v[12:13], off
	v_lshl_add_u64 v[12:13], v[182:183], 0, s[6:7]
	global_load_dwordx2 v[192:193], v[12:13], off
	s_waitcnt vmcnt(24)
	v_mad_u32_u16 v206, v156, v195, v205
	v_mad_u32_u16 v207, v156, v195, v205 op_sel:[1,0,0,0]
	v_mad_u32_u16 v208, v157, v195, v205
	v_mad_u32_u16 v209, v157, v195, v205 op_sel:[1,0,0,0]
	v_mad_u32_u16 v210, v158, v195, v205
	v_mad_u32_u16 v211, v158, v195, v205 op_sel:[1,0,0,0]
	v_mad_u32_u16 v212, v159, v195, v205
	v_mad_u32_u16 v213, v159, v195, v205 op_sel:[1,0,0,0]
	v_mad_u32_u16 v214, v152, v195, v205
	v_mad_u32_u16 v215, v152, v195, v205 op_sel:[1,0,0,0]
	v_mad_u32_u16 v216, v153, v195, v205
	v_mad_u32_u16 v217, v153, v195, v205 op_sel:[1,0,0,0]
	v_mad_u32_u16 v218, v154, v195, v205
	v_mad_u32_u16 v219, v154, v195, v205 op_sel:[1,0,0,0]
	v_mad_u32_u16 v220, v155, v195, v205
	v_mad_u32_u16 v221, v155, v195, v205 op_sel:[1,0,0,0]
	s_add_i32 s6, s53, s8
	s_cmp_gt_i32 s6, 0x101ff
	s_cbranch_scc1 .LBB0_188
; #define PEER_GATHER(TAB, IA, IB, RR) do { _Pragma("unroll") for (int g = 0; g < 16; ++g) { \
;     const unsigned _w = (g < 8 ? IA : IB)[(g >> 1) & 3]; RR[g] = *(const u32x4*)((TAB) + row_off(_w, c16, (g & 1) != 0)); } } while (0)
; DI void phase_peer_v(const Params& p, int layer, int wave) {
;     ...
;     wA = wAb; wB = wBb; hR = hRb;
;     PEER_META_V(t + 3 * nslot, iAb, iBb, wAb, wBb, hRb);
;     PEER_GATHER(vb, iAa, iBa, rrA);
	s_waitcnt vmcnt(21)
	global_load_dwordx4 v[120:123], v206, s[80:81]
	v_cvt_pk_f32_fp8_e32 v[154:155], v148
	v_cvt_pk_f32_fp8_sdwa v[156:157], v148 src0_sel:WORD_1
	v_cvt_pk_f32_fp8_e32 v[158:159], v149
	v_cvt_pk_f32_fp8_sdwa v[148:149], v149 src0_sel:WORD_1
	v_cvt_pk_f32_fp8_e32 v[168:169], v150
	v_cvt_pk_f32_fp8_sdwa v[170:171], v150 src0_sel:WORD_1
	v_cvt_pk_f32_fp8_e32 v[172:173], v151
	v_cvt_pk_f32_fp8_sdwa v[150:151], v151 src0_sel:WORD_1
	v_lshlrev_b32_e32 v152, 16, v72
	v_pk_fma_f32 v[154:155], v[152:153], v[154:155], 0 op_sel_hi:[0,1,0]
	v_pk_fma_f32 v[156:157], v[152:153], v[156:157], 0 op_sel_hi:[0,1,0]
	v_pk_fma_f32 v[158:159], v[152:153], v[158:159], 0 op_sel_hi:[0,1,0]
	v_pk_fma_f32 v[148:149], v[152:153], v[148:149], 0 op_sel_hi:[0,1,0]
	v_pk_fma_f32 v[168:169], v[152:153], v[168:169], 0 op_sel_hi:[0,1,0]
	v_pk_fma_f32 v[170:171], v[152:153], v[170:171], 0 op_sel_hi:[0,1,0]
	v_pk_fma_f32 v[172:173], v[152:153], v[172:173], 0 op_sel_hi:[0,1,0]
	v_pk_fma_f32 v[150:151], v[152:153], v[150:151], 0 op_sel_hi:[0,1,0]
	s_waitcnt vmcnt(21)
	global_load_dwordx4 v[112:115], v207, s[80:81]
	v_cvt_pk_f32_fp8_e32 v[152:153], v144
	v_cvt_pk_f32_fp8_sdwa v[174:175], v144 src0_sel:WORD_1
	v_and_b32_e32 v72, 0xffff0000, v72
	v_pk_fma_f32 v[152:153], v[72:73], v[152:153], v[154:155] op_sel_hi:[0,1,1]
	v_pk_fma_f32 v[154:155], v[72:73], v[174:175], v[156:157] op_sel_hi:[0,1,1]
	v_cvt_pk_f32_fp8_e32 v[156:157], v145
	v_cvt_pk_f32_fp8_sdwa v[144:145], v145 src0_sel:WORD_1
	v_pk_fma_f32 v[156:157], v[72:73], v[156:157], v[158:159] op_sel_hi:[0,1,1]
	v_pk_fma_f32 v[144:145], v[72:73], v[144:145], v[148:149] op_sel_hi:[0,1,1]
	v_cvt_pk_f32_fp8_e32 v[148:149], v146
	v_cvt_pk_f32_fp8_sdwa v[158:159], v146 src0_sel:WORD_1
	v_pk_fma_f32 v[148:149], v[72:73], v[148:149], v[168:169] op_sel_hi:[0,1,1]
	v_cvt_pk_f32_fp8_e32 v[168:169], v147
	v_cvt_pk_f32_fp8_sdwa v[146:147], v147 src0_sel:WORD_1
	v_pk_fma_f32 v[158:159], v[72:73], v[158:159], v[170:171] op_sel_hi:[0,1,1]
	s_waitcnt vmcnt(21)
	global_load_dwordx4 v[104:107], v208, s[80:81]
	v_cvt_pk_f32_fp8_sdwa v[170:171], v136 src0_sel:WORD_1
	v_pk_fma_f32 v[168:169], v[72:73], v[168:169], v[172:173] op_sel_hi:[0,1,1]
	v_pk_fma_f32 v[146:147], v[72:73], v[146:147], v[150:151] op_sel_hi:[0,1,1]
	v_cvt_pk_f32_fp8_e32 v[150:151], v136
	v_lshlrev_b32_e32 v72, 16, v73
	v_pk_fma_f32 v[150:151], v[72:73], v[150:151], v[152:153] op_sel_hi:[0,1,1]
	v_pk_fma_f32 v[152:153], v[72:73], v[170:171], v[154:155] op_sel_hi:[0,1,1]
	v_cvt_pk_f32_fp8_e32 v[154:155], v137
	v_cvt_pk_f32_fp8_sdwa v[136:137], v137 src0_sel:WORD_1
	v_pk_fma_f32 v[154:155], v[72:73], v[154:155], v[156:157] op_sel_hi:[0,1,1]
	v_pk_fma_f32 v[136:137], v[72:73], v[136:137], v[144:145] op_sel_hi:[0,1,1]
	v_cvt_pk_f32_fp8_e32 v[144:145], v138
	v_cvt_pk_f32_fp8_sdwa v[156:157], v138 src0_sel:WORD_1
	v_pk_fma_f32 v[144:145], v[72:73], v[144:145], v[148:149] op_sel_hi:[0,1,1]
	v_pk_fma_f32 v[148:149], v[72:73], v[156:157], v[158:159] op_sel_hi:[0,1,1]
	v_cvt_pk_f32_fp8_e32 v[156:157], v139
	v_cvt_pk_f32_fp8_sdwa v[138:139], v139 src0_sel:WORD_1
	s_waitcnt vmcnt(21)
	global_load_dwordx4 v[96:99], v209, s[80:81]
	v_cvt_pk_f32_fp8_sdwa v[158:159], v132 src0_sel:WORD_1
	v_pk_fma_f32 v[156:157], v[72:73], v[156:157], v[168:169] op_sel_hi:[0,1,1]
	v_pk_fma_f32 v[138:139], v[72:73], v[138:139], v[146:147] op_sel_hi:[0,1,1]
	v_cvt_pk_f32_fp8_e32 v[146:147], v132
	v_and_b32_e32 v72, 0xffff0000, v73
	v_pk_fma_f32 v[146:147], v[72:73], v[146:147], v[150:151] op_sel_hi:[0,1,1]
	v_pk_fma_f32 v[150:151], v[72:73], v[158:159], v[152:153] op_sel_hi:[0,1,1]
	v_cvt_pk_f32_fp8_e32 v[152:153], v133
	v_cvt_pk_f32_fp8_sdwa v[132:133], v133 src0_sel:WORD_1
	v_pk_fma_f32 v[152:153], v[72:73], v[152:153], v[154:155] op_sel_hi:[0,1,1]
	v_pk_fma_f32 v[132:133], v[72:73], v[132:133], v[136:137] op_sel_hi:[0,1,1]
	v_cvt_pk_f32_fp8_e32 v[136:137], v134
	v_cvt_pk_f32_fp8_sdwa v[154:155], v134 src0_sel:WORD_1
	v_pk_fma_f32 v[136:137], v[72:73], v[136:137], v[144:145] op_sel_hi:[0,1,1]
	v_pk_fma_f32 v[144:145], v[72:73], v[154:155], v[148:149] op_sel_hi:[0,1,1]
	v_cvt_pk_f32_fp8_e32 v[148:149], v135
	v_cvt_pk_f32_fp8_sdwa v[134:135], v135 src0_sel:WORD_1
	s_waitcnt vmcnt(21)
	global_load_dwordx4 v[88:91], v210, s[80:81]
	v_cvt_pk_f32_fp8_sdwa v[154:155], v124 src0_sel:WORD_1
	v_pk_fma_f32 v[148:149], v[72:73], v[148:149], v[156:157] op_sel_hi:[0,1,1]
	v_pk_fma_f32 v[72:73], v[72:73], v[134:135], v[138:139] op_sel_hi:[0,1,1]
	v_cvt_pk_f32_fp8_e32 v[138:139], v124
	v_lshlrev_b32_e32 v134, 16, v74
	v_and_b32_e32 v74, 0xffff0000, v74
	v_pk_fma_f32 v[138:139], v[134:135], v[138:139], v[146:147] op_sel_hi:[0,1,1]
	v_pk_fma_f32 v[146:147], v[134:135], v[154:155], v[150:151] op_sel_hi:[0,1,1]
	v_cvt_pk_f32_fp8_e32 v[150:151], v125
	v_cvt_pk_f32_fp8_sdwa v[124:125], v125 src0_sel:WORD_1
	v_pk_fma_f32 v[150:151], v[134:135], v[150:151], v[152:153] op_sel_hi:[0,1,1]
	v_pk_fma_f32 v[124:125], v[134:135], v[124:125], v[132:133] op_sel_hi:[0,1,1]
	v_cvt_pk_f32_fp8_e32 v[132:133], v126
	v_cvt_pk_f32_fp8_sdwa v[152:153], v126 src0_sel:WORD_1
	v_pk_fma_f32 v[132:133], v[134:135], v[132:133], v[136:137] op_sel_hi:[0,1,1]
	v_pk_fma_f32 v[136:137], v[134:135], v[152:153], v[144:145] op_sel_hi:[0,1,1]
	v_cvt_pk_f32_fp8_e32 v[144:145], v127
	v_cvt_pk_f32_fp8_sdwa v[126:127], v127 src0_sel:WORD_1
	v_pk_fma_f32 v[144:145], v[134:135], v[144:145], v[148:149] op_sel_hi:[0,1,1]
	v_pk_fma_f32 v[72:73], v[134:135], v[126:127], v[72:73] op_sel_hi:[0,1,1]
	s_waitcnt vmcnt(21)
	global_load_dwordx4 v[80:83], v211, s[80:81]
	v_cvt_pk_f32_fp8_e32 v[126:127], v116
	v_cvt_pk_f32_fp8_sdwa v[134:135], v116 src0_sel:WORD_1
	v_pk_fma_f32 v[126:127], v[74:75], v[126:127], v[138:139] op_sel_hi:[0,1,1]
	v_cvt_pk_f32_fp8_e32 v[138:139], v117
	v_cvt_pk_f32_fp8_sdwa v[116:117], v117 src0_sel:WORD_1
	v_pk_fma_f32 v[134:135], v[74:75], v[134:135], v[146:147] op_sel_hi:[0,1,1]
	v_cvt_pk_f32_fp8_sdwa v[146:147], v118 src0_sel:WORD_1
	v_pk_fma_f32 v[138:139], v[74:75], v[138:139], v[150:151] op_sel_hi:[0,1,1]
	v_pk_fma_f32 v[116:117], v[74:75], v[116:117], v[124:125] op_sel_hi:[0,1,1]
	v_cvt_pk_f32_fp8_e32 v[124:125], v118
	v_pk_fma_f32 v[124:125], v[74:75], v[124:125], v[132:133] op_sel_hi:[0,1,1]
	v_pk_fma_f32 v[132:133], v[74:75], v[146:147], v[136:137] op_sel_hi:[0,1,1]
	v_cvt_pk_f32_fp8_e32 v[136:137], v119
	v_cvt_pk_f32_fp8_sdwa v[118:119], v119 src0_sel:WORD_1
	v_pk_fma_f32 v[136:137], v[74:75], v[136:137], v[144:145] op_sel_hi:[0,1,1]
	v_pk_fma_f32 v[72:73], v[74:75], v[118:119], v[72:73] op_sel_hi:[0,1,1]
	s_waitcnt vmcnt(21)
	global_load_dwordx4 v[68:71], v212, s[80:81]
	v_cvt_pk_f32_fp8_e32 v[118:119], v108
	v_cvt_pk_f32_fp8_sdwa v[144:145], v108 src0_sel:WORD_1
	v_lshlrev_b32_e32 v74, 16, v75
	v_pk_fma_f32 v[118:119], v[74:75], v[118:119], v[126:127] op_sel_hi:[0,1,1]
	v_pk_fma_f32 v[126:127], v[74:75], v[144:145], v[134:135] op_sel_hi:[0,1,1]
	v_cvt_pk_f32_fp8_e32 v[134:135], v109
	v_cvt_pk_f32_fp8_sdwa v[108:109], v109 src0_sel:WORD_1
	v_pk_fma_f32 v[134:135], v[74:75], v[134:135], v[138:139] op_sel_hi:[0,1,1]
	v_pk_fma_f32 v[108:109], v[74:75], v[108:109], v[116:117] op_sel_hi:[0,1,1]
	v_cvt_pk_f32_fp8_e32 v[116:117], v110
	v_cvt_pk_f32_fp8_sdwa v[138:139], v110 src0_sel:WORD_1
	v_pk_fma_f32 v[116:117], v[74:75], v[116:117], v[124:125] op_sel_hi:[0,1,1]
	v_pk_fma_f32 v[124:125], v[74:75], v[138:139], v[132:133] op_sel_hi:[0,1,1]
	v_cvt_pk_f32_fp8_e32 v[132:133], v111
	v_cvt_pk_f32_fp8_sdwa v[110:111], v111 src0_sel:WORD_1
	v_pk_fma_f32 v[132:133], v[74:75], v[132:133], v[136:137] op_sel_hi:[0,1,1]
	v_pk_fma_f32 v[72:73], v[74:75], v[110:111], v[72:73] op_sel_hi:[0,1,1]
	s_waitcnt vmcnt(21)
	global_load_dwordx4 v[60:63], v213, s[80:81]
	v_cvt_pk_f32_fp8_e32 v[110:111], v100
	v_cvt_pk_f32_fp8_sdwa v[136:137], v100 src0_sel:WORD_1
	v_and_b32_e32 v74, 0xffff0000, v75
	v_pk_fma_f32 v[110:111], v[74:75], v[110:111], v[118:119] op_sel_hi:[0,1,1]
	v_pk_fma_f32 v[118:119], v[74:75], v[136:137], v[126:127] op_sel_hi:[0,1,1]
	v_cvt_pk_f32_fp8_e32 v[126:127], v101
	v_cvt_pk_f32_fp8_sdwa v[100:101], v101 src0_sel:WORD_1
	v_pk_fma_f32 v[126:127], v[74:75], v[126:127], v[134:135] op_sel_hi:[0,1,1]
	v_pk_fma_f32 v[100:101], v[74:75], v[100:101], v[108:109] op_sel_hi:[0,1,1]
	v_cvt_pk_f32_fp8_e32 v[108:109], v102
	v_cvt_pk_f32_fp8_sdwa v[134:135], v102 src0_sel:WORD_1
	v_pk_fma_f32 v[108:109], v[74:75], v[108:109], v[116:117] op_sel_hi:[0,1,1]
	v_pk_fma_f32 v[116:117], v[74:75], v[134:135], v[124:125] op_sel_hi:[0,1,1]
	v_cvt_pk_f32_fp8_e32 v[124:125], v103
	v_cvt_pk_f32_fp8_sdwa v[102:103], v103 src0_sel:WORD_1
	v_pk_fma_f32 v[124:125], v[74:75], v[124:125], v[132:133] op_sel_hi:[0,1,1]
	v_pk_fma_f32 v[72:73], v[74:75], v[102:103], v[72:73] op_sel_hi:[0,1,1]
	s_waitcnt vmcnt(21)
	global_load_dwordx4 v[52:55], v214, s[80:81]
	v_cvt_pk_f32_fp8_e32 v[102:103], v92
	v_cvt_pk_f32_fp8_sdwa v[132:133], v92 src0_sel:WORD_1
	v_lshlrev_b32_e32 v74, 16, v8
	v_and_b32_e32 v8, 0xffff0000, v8
	v_pk_fma_f32 v[102:103], v[74:75], v[102:103], v[110:111] op_sel_hi:[0,1,1]
	v_pk_fma_f32 v[110:111], v[74:75], v[132:133], v[118:119] op_sel_hi:[0,1,1]
	v_cvt_pk_f32_fp8_e32 v[118:119], v93
	v_cvt_pk_f32_fp8_sdwa v[92:93], v93 src0_sel:WORD_1
	v_pk_fma_f32 v[118:119], v[74:75], v[118:119], v[126:127] op_sel_hi:[0,1,1]
	v_pk_fma_f32 v[92:93], v[74:75], v[92:93], v[100:101] op_sel_hi:[0,1,1]
	v_cvt_pk_f32_fp8_e32 v[100:101], v94
	v_cvt_pk_f32_fp8_sdwa v[126:127], v94 src0_sel:WORD_1
	v_pk_fma_f32 v[100:101], v[74:75], v[100:101], v[108:109] op_sel_hi:[0,1,1]
	v_pk_fma_f32 v[108:109], v[74:75], v[126:127], v[116:117] op_sel_hi:[0,1,1]
	v_cvt_pk_f32_fp8_e32 v[116:117], v95
	v_cvt_pk_f32_fp8_sdwa v[94:95], v95 src0_sel:WORD_1
	v_pk_fma_f32 v[116:117], v[74:75], v[116:117], v[124:125] op_sel_hi:[0,1,1]
	v_pk_fma_f32 v[72:73], v[74:75], v[94:95], v[72:73] op_sel_hi:[0,1,1]
	s_waitcnt vmcnt(21)
	global_load_dwordx4 v[40:43], v215, s[80:81]
	v_cvt_pk_f32_fp8_e32 v[74:75], v84
	v_cvt_pk_f32_fp8_sdwa v[94:95], v84 src0_sel:WORD_1
	v_pk_fma_f32 v[74:75], v[8:9], v[74:75], v[102:103] op_sel_hi:[0,1,1]
	v_cvt_pk_f32_fp8_e32 v[102:103], v85
	v_cvt_pk_f32_fp8_sdwa v[84:85], v85 src0_sel:WORD_1
	v_pk_fma_f32 v[94:95], v[8:9], v[94:95], v[110:111] op_sel_hi:[0,1,1]
	v_cvt_pk_f32_fp8_sdwa v[110:111], v86 src0_sel:WORD_1
	v_pk_fma_f32 v[102:103], v[8:9], v[102:103], v[118:119] op_sel_hi:[0,1,1]
	v_pk_fma_f32 v[84:85], v[8:9], v[84:85], v[92:93] op_sel_hi:[0,1,1]
	v_cvt_pk_f32_fp8_e32 v[92:93], v86
	v_pk_fma_f32 v[92:93], v[8:9], v[92:93], v[100:101] op_sel_hi:[0,1,1]
	v_pk_fma_f32 v[100:101], v[8:9], v[110:111], v[108:109] op_sel_hi:[0,1,1]
	v_cvt_pk_f32_fp8_e32 v[108:109], v87
	v_cvt_pk_f32_fp8_sdwa v[86:87], v87 src0_sel:WORD_1
	s_waitcnt vmcnt(21)
	global_load_dwordx4 v[32:35], v216, s[80:81]
	v_cvt_pk_f32_fp8_sdwa v[110:111], v76 src0_sel:WORD_1
	v_pk_fma_f32 v[108:109], v[8:9], v[108:109], v[116:117] op_sel_hi:[0,1,1]
	v_pk_fma_f32 v[72:73], v[8:9], v[86:87], v[72:73] op_sel_hi:[0,1,1]
	v_cvt_pk_f32_fp8_e32 v[86:87], v76
	v_lshlrev_b32_e32 v8, 16, v9
	v_pk_fma_f32 v[74:75], v[8:9], v[86:87], v[74:75] op_sel_hi:[0,1,1]
	v_pk_fma_f32 v[86:87], v[8:9], v[110:111], v[94:95] op_sel_hi:[0,1,1]
	v_cvt_pk_f32_fp8_e32 v[94:95], v77
	v_cvt_pk_f32_fp8_sdwa v[76:77], v77 src0_sel:WORD_1
	v_pk_fma_f32 v[94:95], v[8:9], v[94:95], v[102:103] op_sel_hi:[0,1,1]
	v_pk_fma_f32 v[76:77], v[8:9], v[76:77], v[84:85] op_sel_hi:[0,1,1]
	v_cvt_pk_f32_fp8_e32 v[84:85], v78
	v_cvt_pk_f32_fp8_sdwa v[102:103], v78 src0_sel:WORD_1
	v_pk_fma_f32 v[84:85], v[8:9], v[84:85], v[92:93] op_sel_hi:[0,1,1]
	v_pk_fma_f32 v[92:93], v[8:9], v[102:103], v[100:101] op_sel_hi:[0,1,1]
	v_cvt_pk_f32_fp8_e32 v[100:101], v79
	v_cvt_pk_f32_fp8_sdwa v[78:79], v79 src0_sel:WORD_1
	s_waitcnt vmcnt(21)
	global_load_dwordx4 v[28:31], v217, s[80:81]
	v_cvt_pk_f32_fp8_sdwa v[102:103], v64 src0_sel:WORD_1
	v_pk_fma_f32 v[100:101], v[8:9], v[100:101], v[108:109] op_sel_hi:[0,1,1]
	v_pk_fma_f32 v[72:73], v[8:9], v[78:79], v[72:73] op_sel_hi:[0,1,1]
	v_cvt_pk_f32_fp8_e32 v[78:79], v64
	v_and_b32_e32 v8, 0xffff0000, v9
	v_pk_fma_f32 v[74:75], v[8:9], v[78:79], v[74:75] op_sel_hi:[0,1,1]
	v_pk_fma_f32 v[78:79], v[8:9], v[102:103], v[86:87] op_sel_hi:[0,1,1]
	v_cvt_pk_f32_fp8_e32 v[86:87], v65
	v_cvt_pk_f32_fp8_sdwa v[64:65], v65 src0_sel:WORD_1
	v_pk_fma_f32 v[86:87], v[8:9], v[86:87], v[94:95] op_sel_hi:[0,1,1]
	v_pk_fma_f32 v[64:65], v[8:9], v[64:65], v[76:77] op_sel_hi:[0,1,1]
	v_cvt_pk_f32_fp8_e32 v[76:77], v66
	v_cvt_pk_f32_fp8_sdwa v[94:95], v66 src0_sel:WORD_1
	v_pk_fma_f32 v[76:77], v[8:9], v[76:77], v[84:85] op_sel_hi:[0,1,1]
	v_pk_fma_f32 v[84:85], v[8:9], v[94:95], v[92:93] op_sel_hi:[0,1,1]
	v_cvt_pk_f32_fp8_e32 v[92:93], v67
	v_cvt_pk_f32_fp8_sdwa v[66:67], v67 src0_sel:WORD_1
	s_waitcnt vmcnt(21)
	global_load_dwordx4 v[24:27], v218, s[80:81]
	v_cvt_pk_f32_fp8_sdwa v[94:95], v56 src0_sel:WORD_1
	v_pk_fma_f32 v[92:93], v[8:9], v[92:93], v[100:101] op_sel_hi:[0,1,1]
	v_pk_fma_f32 v[8:9], v[8:9], v[66:67], v[72:73] op_sel_hi:[0,1,1]
	v_cvt_pk_f32_fp8_e32 v[72:73], v56
	v_lshlrev_b32_e32 v66, 16, v10
	v_and_b32_e32 v10, 0xffff0000, v10
	v_pk_fma_f32 v[72:73], v[66:67], v[72:73], v[74:75] op_sel_hi:[0,1,1]
	v_pk_fma_f32 v[74:75], v[66:67], v[94:95], v[78:79] op_sel_hi:[0,1,1]
	v_cvt_pk_f32_fp8_e32 v[78:79], v57
	v_cvt_pk_f32_fp8_sdwa v[56:57], v57 src0_sel:WORD_1
	v_pk_fma_f32 v[78:79], v[66:67], v[78:79], v[86:87] op_sel_hi:[0,1,1]
	v_pk_fma_f32 v[56:57], v[66:67], v[56:57], v[64:65] op_sel_hi:[0,1,1]
	v_cvt_pk_f32_fp8_e32 v[64:65], v58
	v_cvt_pk_f32_fp8_sdwa v[86:87], v58 src0_sel:WORD_1
	v_pk_fma_f32 v[64:65], v[66:67], v[64:65], v[76:77] op_sel_hi:[0,1,1]
	v_pk_fma_f32 v[76:77], v[66:67], v[86:87], v[84:85] op_sel_hi:[0,1,1]
	v_cvt_pk_f32_fp8_e32 v[84:85], v59
	v_cvt_pk_f32_fp8_sdwa v[58:59], v59 src0_sel:WORD_1
	v_pk_fma_f32 v[84:85], v[66:67], v[84:85], v[92:93] op_sel_hi:[0,1,1]
	v_pk_fma_f32 v[8:9], v[66:67], v[58:59], v[8:9] op_sel_hi:[0,1,1]
	s_waitcnt vmcnt(21)
	global_load_dwordx4 v[20:23], v219, s[80:81]
	v_cvt_pk_f32_fp8_e32 v[58:59], v48
	v_cvt_pk_f32_fp8_sdwa v[66:67], v48 src0_sel:WORD_1
	v_pk_fma_f32 v[58:59], v[10:11], v[58:59], v[72:73] op_sel_hi:[0,1,1]
	v_cvt_pk_f32_fp8_e32 v[72:73], v49
	v_cvt_pk_f32_fp8_sdwa v[48:49], v49 src0_sel:WORD_1
	v_pk_fma_f32 v[66:67], v[10:11], v[66:67], v[74:75] op_sel_hi:[0,1,1]
	v_cvt_pk_f32_fp8_sdwa v[74:75], v50 src0_sel:WORD_1
	v_pk_fma_f32 v[72:73], v[10:11], v[72:73], v[78:79] op_sel_hi:[0,1,1]
	v_pk_fma_f32 v[48:49], v[10:11], v[48:49], v[56:57] op_sel_hi:[0,1,1]
	v_cvt_pk_f32_fp8_e32 v[56:57], v50
	v_pk_fma_f32 v[56:57], v[10:11], v[56:57], v[64:65] op_sel_hi:[0,1,1]
	v_pk_fma_f32 v[64:65], v[10:11], v[74:75], v[76:77] op_sel_hi:[0,1,1]
	v_cvt_pk_f32_fp8_e32 v[74:75], v51
	v_cvt_pk_f32_fp8_sdwa v[50:51], v51 src0_sel:WORD_1
	s_waitcnt vmcnt(21)
	global_load_dwordx4 v[12:15], v220, s[80:81]
	v_cvt_pk_f32_fp8_sdwa v[76:77], v44 src0_sel:WORD_1
	v_pk_fma_f32 v[74:75], v[10:11], v[74:75], v[84:85] op_sel_hi:[0,1,1]
	v_pk_fma_f32 v[8:9], v[10:11], v[50:51], v[8:9] op_sel_hi:[0,1,1]
	v_cvt_pk_f32_fp8_e32 v[50:51], v44
	v_lshlrev_b32_e32 v10, 16, v11
	v_pk_fma_f32 v[50:51], v[10:11], v[50:51], v[58:59] op_sel_hi:[0,1,1]
	v_pk_fma_f32 v[58:59], v[10:11], v[76:77], v[66:67] op_sel_hi:[0,1,1]
	v_cvt_pk_f32_fp8_e32 v[66:67], v45
	v_cvt_pk_f32_fp8_sdwa v[44:45], v45 src0_sel:WORD_1
	v_pk_fma_f32 v[66:67], v[10:11], v[66:67], v[72:73] op_sel_hi:[0,1,1]
	v_pk_fma_f32 v[44:45], v[10:11], v[44:45], v[48:49] op_sel_hi:[0,1,1]
	v_cvt_pk_f32_fp8_e32 v[48:49], v46
	v_cvt_pk_f32_fp8_sdwa v[72:73], v46 src0_sel:WORD_1
	v_pk_fma_f32 v[48:49], v[10:11], v[48:49], v[56:57] op_sel_hi:[0,1,1]
	v_pk_fma_f32 v[56:57], v[10:11], v[72:73], v[64:65] op_sel_hi:[0,1,1]
	v_cvt_pk_f32_fp8_e32 v[64:65], v47
	v_cvt_pk_f32_fp8_sdwa v[46:47], v47 src0_sel:WORD_1
	s_waitcnt vmcnt(21)
	global_load_dwordx4 v[16:19], v221, s[80:81]
	v_cvt_pk_f32_fp8_sdwa v[72:73], v36 src0_sel:WORD_1
	v_pk_fma_f32 v[64:65], v[10:11], v[64:65], v[74:75] op_sel_hi:[0,1,1]
	v_pk_fma_f32 v[8:9], v[10:11], v[46:47], v[8:9] op_sel_hi:[0,1,1]
	v_cvt_pk_f32_fp8_e32 v[46:47], v36
	v_and_b32_e32 v10, 0xffff0000, v11
	v_pk_fma_f32 v[46:47], v[10:11], v[46:47], v[50:51] op_sel_hi:[0,1,1]
	v_pk_fma_f32 v[50:51], v[10:11], v[72:73], v[58:59] op_sel_hi:[0,1,1]
	v_cvt_pk_f32_fp8_e32 v[58:59], v37
	v_cvt_pk_f32_fp8_sdwa v[36:37], v37 src0_sel:WORD_1
	v_pk_fma_f32 v[58:59], v[10:11], v[58:59], v[66:67] op_sel_hi:[0,1,1]
	v_pk_fma_f32 v[36:37], v[10:11], v[36:37], v[44:45] op_sel_hi:[0,1,1]
	v_cvt_pk_f32_fp8_e32 v[44:45], v38
	v_cvt_pk_f32_fp8_sdwa v[66:67], v38 src0_sel:WORD_1
	v_pk_fma_f32 v[44:45], v[10:11], v[44:45], v[48:49] op_sel_hi:[0,1,1]
	v_pk_fma_f32 v[48:49], v[10:11], v[66:67], v[56:57] op_sel_hi:[0,1,1]
	v_cvt_pk_f32_fp8_e32 v[56:57], v39
	v_cvt_pk_f32_fp8_sdwa v[38:39], v39 src0_sel:WORD_1
	v_permlane32_swap_b32_e32 v46, v44
	v_pk_fma_f32 v[56:57], v[10:11], v[56:57], v[64:65] op_sel_hi:[0,1,1]
	v_pk_fma_f32 v[8:9], v[10:11], v[38:39], v[8:9] op_sel_hi:[0,1,1]
	v_permlane32_swap_b32_e32 v47, v45
	v_permlane32_swap_b32_e32 v50, v48
	v_permlane32_swap_b32_e32 v51, v49
	v_permlane32_swap_b32_e32 v58, v56
	v_permlane32_swap_b32_e32 v59, v57
	v_permlane32_swap_b32_e32 v36, v8
	v_permlane32_swap_b32_e32 v37, v9
	v_add_f32_e32 v10, v46, v44
	v_add_f32_e32 v11, v47, v45
	v_add_f32_e32 v38, v50, v48
	v_add_f32_e32 v39, v51, v49
	v_add_f32_e32 v44, v58, v56
	v_add_f32_e32 v45, v59, v57
	v_add_f32_e32 v36, v36, v8
	v_add_f32_e32 v37, v37, v9
	v_permlane16_swap_b32_e32 v10, v44
	v_permlane16_swap_b32_e32 v11, v45
	v_permlane16_swap_b32_e32 v38, v36
	v_permlane16_swap_b32_e32 v39, v37
	v_pk_add_f32 v[8:9], v[10:11], v[44:45]
	v_pk_add_f32 v[10:11], v[38:39], v[36:37]
	s_nop 0
	v_mov_b32_dpp v38, v8 row_ror:8 row_mask:0xf bank_mask:0xf bound_ctrl:1
	v_mov_b32_dpp v39, v9 row_ror:8 row_mask:0xf bank_mask:0xf bound_ctrl:1
	v_mov_b32_dpp v36, v10 row_ror:8 row_mask:0xf bank_mask:0xf bound_ctrl:1
	v_mov_b32_dpp v37, v11 row_ror:8 row_mask:0xf bank_mask:0xf bound_ctrl:1
	s_and_saveexec_b64 s[8:9], s[0:1]
	s_cbranch_execz .LBB0_187
	v_pk_add_f32 v[8:9], v[8:9], v[38:39]
	v_lshlrev_b32_e32 v38, 16, v186
	v_and_b32_e32 v39, 0xffff0000, v186
	v_pk_add_f32 v[10:11], v[10:11], v[36:37]
	v_lshlrev_b32_e32 v36, 16, v187
	v_and_b32_e32 v37, 0xffff0000, v187
	s_ashr_i32 s7, s6, 31
	v_pk_fma_f32 v[8:9], v[38:39], s[86:87], v[8:9] op_sel_hi:[1,0,1]
	v_pk_fma_f32 v[10:11], v[36:37], s[86:87], v[10:11] op_sel_hi:[1,0,1]
	s_lshl_b64 s[6:7], s[6:7], 11
	v_cvt_pk_bf16_f32 v8, v8, v9
	v_cvt_pk_bf16_f32 v9, v10, v11
	v_lshl_add_u64 v[10:11], v[184:185], 0, s[6:7]
	global_store_dwordx2 v[10:11], v[8:9], off
	s_branch .LBB0_187

; __global__ void __launch_bounds__(NTHREADS, 2) mega(Params p) {
;   extern __shared__ __attribute__((aligned(16))) char smem[];
;   cg::grid_group grid = cg::this_grid();
;   const int wave = __builtin_amdgcn_readfirstlane((int)(threadIdx.x >> 6));
	.amdhsa_kernel _Z4mega6Params
		.amdhsa_group_segment_fixed_size 0
		.amdhsa_private_segment_fixed_size 0
		.amdhsa_kernarg_size 440
		.amdhsa_user_sgpr_count 2
		.amdhsa_user_sgpr_dispatch_ptr 0
		.amdhsa_user_sgpr_queue_ptr 0
		.amdhsa_user_sgpr_kernarg_segment_ptr 1
		.amdhsa_user_sgpr_dispatch_id 0
		.amdhsa_user_sgpr_kernarg_preload_length 0
		.amdhsa_user_sgpr_kernarg_preload_offset 0
		.amdhsa_user_sgpr_private_segment_size 0
		.amdhsa_uses_dynamic_stack 0
		.amdhsa_enable_private_segment 0
		.amdhsa_system_sgpr_workgroup_id_x 1
		.amdhsa_system_sgpr_workgroup_id_y 0
		.amdhsa_system_sgpr_workgroup_id_z 0
		.amdhsa_system_sgpr_workgroup_info 0
		.amdhsa_system_vgpr_workitem_id 2
		.amdhsa_next_free_vgpr 256
		.amdhsa_next_free_sgpr 102
		.amdhsa_accum_offset 256
		.amdhsa_reserve_vcc 1
		.amdhsa_float_round_mode_32 0
		.amdhsa_float_round_mode_16_64 0
		.amdhsa_float_denorm_mode_32 3
		.amdhsa_float_denorm_mode_16_64 3
		.amdhsa_dx10_clamp 1
		.amdhsa_ieee_mode 1
		.amdhsa_fp16_overflow 0
		.amdhsa_tg_split 0
		.amdhsa_exception_fp_ieee_invalid_op 0
		.amdhsa_exception_fp_denorm_src 0
		.amdhsa_exception_fp_ieee_div_zero 0
		.amdhsa_exception_fp_ieee_overflow 0
		.amdhsa_exception_fp_ieee_underflow 0
		.amdhsa_exception_fp_ieee_inexact 0
		.amdhsa_exception_int_div_zero 0
	.end_amdhsa_kernel

; __global__ void __launch_bounds__(NTHREADS, 2) mega(Params p) {
;   extern __shared__ __attribute__((aligned(16))) char smem[];
;   cg::grid_group grid = cg::this_grid();
;   const int wave = __builtin_amdgcn_readfirstlane((int)(threadIdx.x >> 6));
amdhsa.kernels:
  - .agpr_count:     0
    .args:
      - .offset:         0
        .size:           184
        .value_kind:     by_value
      - .offset:         184
        .size:           4
        .value_kind:     hidden_block_count_x
      - .offset:         188
        .size:           4
        .value_kind:     hidden_block_count_y
      - .offset:         192
        .size:           4
        .value_kind:     hidden_block_count_z
      - .offset:         196
        .size:           2
        .value_kind:     hidden_group_size_x
      - .offset:         198
        .size:           2
        .value_kind:     hidden_group_size_y
      - .offset:         200
        .size:           2
        .value_kind:     hidden_group_size_z
      - .offset:         202
        .size:           2
        .value_kind:     hidden_remainder_x
      - .offset:         204
        .size:           2
        .value_kind:     hidden_remainder_y
      - .offset:         206
        .size:           2
        .value_kind:     hidden_remainder_z
      - .offset:         224
        .size:           8
        .value_kind:     hidden_global_offset_x
      - .offset:         232
        .size:           8
        .value_kind:     hidden_global_offset_y
      - .offset:         240
        .size:           8
        .value_kind:     hidden_global_offset_z
      - .offset:         248
        .size:           2
        .value_kind:     hidden_grid_dims
      - .offset:         272
        .size:           8
        .value_kind:     hidden_multigrid_sync_arg
      - .offset:         304
        .size:           4
        .value_kind:     hidden_dynamic_lds_size
    .group_segment_fixed_size: 0
    .kernarg_segment_align: 8
    .kernarg_segment_size: 440
    .language:       OpenCL C
    .language_version:
      - 2
      - 0
    .max_flat_workgroup_size: 512
    .name:           _Z4mega6Params
    .private_segment_fixed_size: 0
    .sgpr_count:     108
    .sgpr_spill_count: 174
    .symbol:         _Z4mega6Params.kd
    .uniform_work_group_size: 1
    .uses_dynamic_stack: false
    .vgpr_count:     256
    .vgpr_spill_count: 0
    .wavefront_size: 64
